# GEMM K-loops: staging loads issued before the fragment ds_reads in every phase's load segment (more flight time for the staged tiles)
# speedup vs baseline: 1.0061x; 1.0061x over previous
.LBB0_206:
	s_add_u32 s24, s22, 0xfffc0080
	s_addc_u32 s25, s23, -1
	s_add_i32 s62, 0, 0x10000
	s_cmp_eq_u32 s61, 12
	s_cselect_b32 s27, s19, s25
	s_cselect_b32 s26, s18, s24
	s_cselect_b32 s25, s21, s17
	s_cselect_b32 s24, s20, s15
	s_add_i32 s64, 0, 0x14000
	v_lshl_add_u64 v[174:175], s[22:23], 0, v[172:173]
	s_add_i32 m0, s34, 0xc000
	global_load_lds_dwordx4 v[174:175], off
	v_lshl_add_u64 v[174:175], s[22:23], 0, v[130:131]
	s_add_i32 m0, s34, 0xe000
	s_nop 0
	global_load_lds_dwordx4 v[174:175], off
	v_add_u32_e32 v148, s62, v134
	v_add_u32_e32 v164, s64, v134
	ds_read_b128 v[136:139], v148
	ds_read_b128 v[140:143], v148 offset:1024
	ds_read_b128 v[144:147], v148 offset:2048
	ds_read_b128 v[148:151], v148 offset:3072
	ds_read_b128 v[152:155], v164
	ds_read_b128 v[156:159], v164 offset:1024
	ds_read_b128 v[160:163], v164 offset:2048
	ds_read_b128 v[164:167], v164 offset:3072
	ds_read_b128 v[168:171], v135
	ds_read_b128 v[188:191], v135 offset:1024
	ds_read_b128 v[204:207], v135 offset:2048
	ds_read_b128 v[208:211], v135 offset:3072
	ds_read_b128 v[212:215], v135 offset:4096
	ds_read_b128 v[216:219], v135 offset:5120
	ds_read_b128 v[220:223], v135 offset:6144
	ds_read_b128 v[224:227], v135 offset:7168
	s_waitcnt vmcnt(8)
	s_waitcnt lgkmcnt(0)
	s_barrier
	s_setprio 1
	s_waitcnt lgkmcnt(0)
	v_mfma_f32_16x16x32_bf16 v[124:127], v[136:139], v[168:171], v[124:127]
	v_mfma_f32_16x16x32_bf16 v[120:123], v[144:147], v[168:171], v[120:123]
	v_mfma_f32_16x16x32_bf16 v[116:119], v[136:139], v[204:207], v[116:119]
	v_mfma_f32_16x16x32_bf16 v[108:111], v[144:147], v[204:207], v[108:111]
	v_mfma_f32_16x16x32_bf16 v[100:103], v[136:139], v[212:215], v[100:103]
	v_mfma_f32_16x16x32_bf16 v[92:95], v[144:147], v[212:215], v[92:95]
	v_mfma_f32_16x16x32_bf16 v[84:87], v[136:139], v[220:223], v[84:87]
	v_mfma_f32_16x16x32_bf16 v[76:79], v[144:147], v[220:223], v[76:79]
	v_mfma_f32_16x16x32_bf16 v[124:127], v[140:143], v[188:191], v[124:127]
	v_mfma_f32_16x16x32_bf16 v[120:123], v[148:151], v[188:191], v[120:123]
	v_mfma_f32_16x16x32_bf16 v[116:119], v[140:143], v[208:211], v[116:119]
	v_mfma_f32_16x16x32_bf16 v[108:111], v[148:151], v[208:211], v[108:111]
	v_mfma_f32_16x16x32_bf16 v[100:103], v[140:143], v[216:219], v[100:103]
	v_mfma_f32_16x16x32_bf16 v[92:95], v[148:151], v[216:219], v[92:95]
	v_mfma_f32_16x16x32_bf16 v[84:87], v[140:143], v[224:227], v[84:87]
	v_mfma_f32_16x16x32_bf16 v[76:79], v[148:151], v[224:227], v[76:79]
	s_setprio 0
	s_setprio 1
	v_mfma_f32_16x16x32_bf16 v[112:115], v[152:155], v[168:171], v[112:115]
	v_mfma_f32_16x16x32_bf16 v[104:107], v[160:163], v[168:171], v[104:107]
	v_mfma_f32_16x16x32_bf16 v[96:99], v[152:155], v[204:207], v[96:99]
	v_mfma_f32_16x16x32_bf16 v[88:91], v[160:163], v[204:207], v[88:91]
	v_mfma_f32_16x16x32_bf16 v[80:83], v[152:155], v[212:215], v[80:83]
	v_mfma_f32_16x16x32_bf16 v[72:75], v[160:163], v[212:215], v[72:75]
	v_mfma_f32_16x16x32_bf16 v[68:71], v[152:155], v[220:223], v[68:71]
	v_mfma_f32_16x16x32_bf16 v[64:67], v[160:163], v[220:223], v[64:67]
	v_mfma_f32_16x16x32_bf16 v[112:115], v[156:159], v[188:191], v[112:115]
	v_mfma_f32_16x16x32_bf16 v[104:107], v[164:167], v[188:191], v[104:107]
	v_mfma_f32_16x16x32_bf16 v[96:99], v[156:159], v[208:211], v[96:99]
	v_mfma_f32_16x16x32_bf16 v[88:91], v[164:167], v[208:211], v[88:91]
	v_mfma_f32_16x16x32_bf16 v[80:83], v[156:159], v[216:219], v[80:83]
	v_mfma_f32_16x16x32_bf16 v[72:75], v[164:167], v[216:219], v[72:75]
	v_mfma_f32_16x16x32_bf16 v[68:71], v[156:159], v[224:227], v[68:71]
	v_mfma_f32_16x16x32_bf16 v[64:67], v[164:167], v[224:227], v[64:67]
	s_setprio 0
	s_barrier
	s_add_i32 s62, s62, s31
	v_lshl_add_u64 v[174:175], s[24:25], 0, v[128:129]
	s_mov_b32 m0, s62
	global_load_lds_dwordx4 v[174:175], off
	s_add_i32 m0, s62, 0x2000
	s_add_u32 s62, s24, 0x40000
	v_lshl_add_u64 v[176:177], s[24:25], 0, v[132:133]
	s_addc_u32 s63, s25, 0
	s_add_i32 s64, s64, s31
	global_load_lds_dwordx4 v[176:177], off
	v_lshl_add_u64 v[180:181], s[62:63], 0, v[128:129]
	s_mov_b32 m0, s64
	v_lshl_add_u64 v[182:183], s[26:27], 0, v[130:131]
	global_load_lds_dwordx4 v[180:181], off
	v_lshl_add_u64 v[180:181], s[62:63], 0, v[132:133]
	s_add_i32 m0, s64, 0x2000
	s_nop 0
	global_load_lds_dwordx4 v[180:181], off
	v_lshl_add_u64 v[180:181], s[26:27], 0, v[172:173]
	s_mov_b32 m0, s34
	s_nop 0
	global_load_lds_dwordx4 v[180:181], off
	s_mov_b32 m0, s35
	s_nop 0
	global_load_lds_dwordx4 v[182:183], off
	ds_read_b128 v[168:171], v135 offset:16384
	ds_read_b128 v[188:191], v135 offset:17408
	ds_read_b128 v[204:207], v135 offset:18432
	ds_read_b128 v[208:211], v135 offset:19456
	ds_read_b128 v[212:215], v135 offset:20480
	ds_read_b128 v[216:219], v135 offset:21504
	ds_read_b128 v[220:223], v135 offset:22528
	ds_read_b128 v[224:227], v135 offset:23552
	s_waitcnt vmcnt(8)
	s_waitcnt lgkmcnt(0)
	s_barrier
	s_setprio 1
	s_waitcnt lgkmcnt(0)
	v_mfma_f32_16x16x32_bf16 v[60:63], v[136:139], v[168:171], v[60:63]
	v_mfma_f32_16x16x32_bf16 v[56:59], v[144:147], v[168:171], v[56:59]
	v_mfma_f32_16x16x32_bf16 v[52:55], v[136:139], v[204:207], v[52:55]
	v_mfma_f32_16x16x32_bf16 v[44:47], v[144:147], v[204:207], v[44:47]
	v_mfma_f32_16x16x32_bf16 v[36:39], v[136:139], v[212:215], v[36:39]
	v_mfma_f32_16x16x32_bf16 v[28:31], v[144:147], v[212:215], v[28:31]
	v_mfma_f32_16x16x32_bf16 v[20:23], v[136:139], v[220:223], v[20:23]
	v_mfma_f32_16x16x32_bf16 v[12:15], v[144:147], v[220:223], v[12:15]
	v_mfma_f32_16x16x32_bf16 v[60:63], v[140:143], v[188:191], v[60:63]
	v_mfma_f32_16x16x32_bf16 v[56:59], v[148:151], v[188:191], v[56:59]
	v_mfma_f32_16x16x32_bf16 v[52:55], v[140:143], v[208:211], v[52:55]
	v_mfma_f32_16x16x32_bf16 v[44:47], v[148:151], v[208:211], v[44:47]
	v_mfma_f32_16x16x32_bf16 v[36:39], v[140:143], v[216:219], v[36:39]
	v_mfma_f32_16x16x32_bf16 v[28:31], v[148:151], v[216:219], v[28:31]
	v_mfma_f32_16x16x32_bf16 v[20:23], v[140:143], v[224:227], v[20:23]
	v_mfma_f32_16x16x32_bf16 v[12:15], v[148:151], v[224:227], v[12:15]
	s_setprio 0
	s_setprio 1
	v_mfma_f32_16x16x32_bf16 v[48:51], v[152:155], v[168:171], v[48:51]
	v_mfma_f32_16x16x32_bf16 v[40:43], v[160:163], v[168:171], v[40:43]
	v_mfma_f32_16x16x32_bf16 v[32:35], v[152:155], v[204:207], v[32:35]
	v_mfma_f32_16x16x32_bf16 v[24:27], v[160:163], v[204:207], v[24:27]
	v_mfma_f32_16x16x32_bf16 v[16:19], v[152:155], v[212:215], v[16:19]
	v_mfma_f32_16x16x32_bf16 v[8:11], v[160:163], v[212:215], v[8:11]
	v_mfma_f32_16x16x32_bf16 v[4:7], v[152:155], v[220:223], v[4:7]
	v_mfma_f32_16x16x32_bf16 v[0:3], v[160:163], v[220:223], v[0:3]
	v_mfma_f32_16x16x32_bf16 v[48:51], v[156:159], v[188:191], v[48:51]
	v_mfma_f32_16x16x32_bf16 v[40:43], v[164:167], v[188:191], v[40:43]
	v_mfma_f32_16x16x32_bf16 v[32:35], v[156:159], v[208:211], v[32:35]
	v_mfma_f32_16x16x32_bf16 v[24:27], v[164:167], v[208:211], v[24:27]
	v_mfma_f32_16x16x32_bf16 v[16:19], v[156:159], v[216:219], v[16:19]
	v_mfma_f32_16x16x32_bf16 v[8:11], v[164:167], v[216:219], v[8:11]
	v_mfma_f32_16x16x32_bf16 v[4:7], v[156:159], v[224:227], v[4:7]
	v_mfma_f32_16x16x32_bf16 v[0:3], v[164:167], v[224:227], v[0:3]
	s_setprio 0
	s_barrier
	s_add_i32 s62, 0, 0x18000
	s_add_i32 s63, 0, 0x1c000
	s_add_u32 s26, s26, 0x40000
	s_addc_u32 s27, s27, 0
	s_mov_b32 m0, s36
	v_lshl_add_u64 v[228:229], s[26:27], 0, v[172:173]
	global_load_lds_dwordx4 v[228:229], off
	v_lshl_add_u64 v[228:229], s[26:27], 0, v[130:131]
	s_mov_b32 m0, s37
	s_nop 0
	global_load_lds_dwordx4 v[228:229], off
	v_add_u32_e32 v148, s62, v134
	v_add_u32_e32 v164, s63, v134
	ds_read_b128 v[136:139], v148
	ds_read_b128 v[140:143], v148 offset:1024
	ds_read_b128 v[144:147], v148 offset:2048
	ds_read_b128 v[148:151], v148 offset:3072
	ds_read_b128 v[152:155], v164
	ds_read_b128 v[156:159], v164 offset:1024
	ds_read_b128 v[160:163], v164 offset:2048
	ds_read_b128 v[164:167], v164 offset:3072
	ds_read_b128 v[168:171], v135 offset:32768
	ds_read_b128 v[188:191], v135 offset:33792
	ds_read_b128 v[204:207], v135 offset:34816
	ds_read_b128 v[208:211], v135 offset:35840
	ds_read_b128 v[212:215], v135 offset:36864
	ds_read_b128 v[216:219], v135 offset:37888
	ds_read_b128 v[220:223], v135 offset:38912
	ds_read_b128 v[224:227], v135 offset:39936
	s_waitcnt vmcnt(8)
	s_waitcnt lgkmcnt(0)
	s_barrier
	s_setprio 1
	s_waitcnt lgkmcnt(0)
	v_mfma_f32_16x16x32_bf16 v[124:127], v[136:139], v[168:171], v[124:127]
	v_mfma_f32_16x16x32_bf16 v[120:123], v[144:147], v[168:171], v[120:123]
	v_mfma_f32_16x16x32_bf16 v[116:119], v[136:139], v[204:207], v[116:119]
	v_mfma_f32_16x16x32_bf16 v[108:111], v[144:147], v[204:207], v[108:111]
	v_mfma_f32_16x16x32_bf16 v[100:103], v[136:139], v[212:215], v[100:103]
	v_mfma_f32_16x16x32_bf16 v[92:95], v[144:147], v[212:215], v[92:95]
	v_mfma_f32_16x16x32_bf16 v[84:87], v[136:139], v[220:223], v[84:87]
	v_mfma_f32_16x16x32_bf16 v[76:79], v[144:147], v[220:223], v[76:79]
	v_mfma_f32_16x16x32_bf16 v[124:127], v[140:143], v[188:191], v[124:127]
	v_mfma_f32_16x16x32_bf16 v[120:123], v[148:151], v[188:191], v[120:123]
	v_mfma_f32_16x16x32_bf16 v[116:119], v[140:143], v[208:211], v[116:119]
	v_mfma_f32_16x16x32_bf16 v[108:111], v[148:151], v[208:211], v[108:111]
	v_mfma_f32_16x16x32_bf16 v[100:103], v[140:143], v[216:219], v[100:103]
	v_mfma_f32_16x16x32_bf16 v[92:95], v[148:151], v[216:219], v[92:95]
	v_mfma_f32_16x16x32_bf16 v[84:87], v[140:143], v[224:227], v[84:87]
	v_mfma_f32_16x16x32_bf16 v[76:79], v[148:151], v[224:227], v[76:79]
	s_setprio 0
	s_setprio 1
	v_mfma_f32_16x16x32_bf16 v[112:115], v[152:155], v[168:171], v[112:115]
	v_mfma_f32_16x16x32_bf16 v[104:107], v[160:163], v[168:171], v[104:107]
	v_mfma_f32_16x16x32_bf16 v[96:99], v[152:155], v[204:207], v[96:99]
	v_mfma_f32_16x16x32_bf16 v[88:91], v[160:163], v[204:207], v[88:91]
	v_mfma_f32_16x16x32_bf16 v[80:83], v[152:155], v[212:215], v[80:83]
	v_mfma_f32_16x16x32_bf16 v[72:75], v[160:163], v[212:215], v[72:75]
	v_mfma_f32_16x16x32_bf16 v[68:71], v[152:155], v[220:223], v[68:71]
	v_mfma_f32_16x16x32_bf16 v[64:67], v[160:163], v[220:223], v[64:67]
	v_mfma_f32_16x16x32_bf16 v[112:115], v[156:159], v[188:191], v[112:115]
	v_mfma_f32_16x16x32_bf16 v[104:107], v[164:167], v[188:191], v[104:107]
	v_mfma_f32_16x16x32_bf16 v[96:99], v[156:159], v[208:211], v[96:99]
	v_mfma_f32_16x16x32_bf16 v[88:91], v[164:167], v[208:211], v[88:91]
	v_mfma_f32_16x16x32_bf16 v[80:83], v[156:159], v[216:219], v[80:83]
	v_mfma_f32_16x16x32_bf16 v[72:75], v[164:167], v[216:219], v[72:75]
	v_mfma_f32_16x16x32_bf16 v[68:71], v[156:159], v[224:227], v[68:71]
	v_mfma_f32_16x16x32_bf16 v[64:67], v[164:167], v[224:227], v[64:67]
	s_setprio 0
	s_barrier
	s_add_i32 s26, s62, s31
	v_lshl_add_u64 v[174:175], v[174:175], 0, s[94:95]
	s_mov_b32 m0, s26
	global_load_lds_dwordx4 v[174:175], off
	s_add_i32 m0, s26, 0x2000
	s_add_u32 s24, s24, 0x40080
	v_lshl_add_u64 v[174:175], v[176:177], 0, s[94:95]
	s_addc_u32 s25, s25, 0
	s_add_i32 s26, s63, s31
	global_load_lds_dwordx4 v[174:175], off
	v_lshl_add_u64 v[174:175], s[24:25], 0, v[128:129]
	s_mov_b32 m0, s26
	s_nop 0
	global_load_lds_dwordx4 v[174:175], off
	v_lshl_add_u64 v[174:175], s[24:25], 0, v[132:133]
	s_add_i32 m0, s26, 0x2000
	s_nop 0
	global_load_lds_dwordx4 v[174:175], off
	v_lshl_add_u64 v[174:175], v[180:181], 0, s[94:95]
	s_mov_b32 m0, s54
	s_nop 0
	global_load_lds_dwordx4 v[174:175], off
	v_lshl_add_u64 v[174:175], v[182:183], 0, s[94:95]
	s_mov_b32 m0, s55
	s_nop 0
	global_load_lds_dwordx4 v[174:175], off
	ds_read_b128 v[168:171], v135 offset:49152
	ds_read_b128 v[188:191], v135 offset:50176
	ds_read_b128 v[204:207], v135 offset:51200
	ds_read_b128 v[208:211], v135 offset:52224
	ds_read_b128 v[212:215], v135 offset:53248
	ds_read_b128 v[216:219], v135 offset:54272
	ds_read_b128 v[220:223], v135 offset:55296
	ds_read_b128 v[224:227], v135 offset:56320
	s_waitcnt vmcnt(8)
	s_waitcnt lgkmcnt(0)
	s_barrier
	s_setprio 1
	s_waitcnt lgkmcnt(0)
	v_mfma_f32_16x16x32_bf16 v[60:63], v[136:139], v[168:171], v[60:63]
	v_mfma_f32_16x16x32_bf16 v[56:59], v[144:147], v[168:171], v[56:59]
	v_mfma_f32_16x16x32_bf16 v[52:55], v[136:139], v[204:207], v[52:55]
	v_mfma_f32_16x16x32_bf16 v[44:47], v[144:147], v[204:207], v[44:47]
	v_mfma_f32_16x16x32_bf16 v[36:39], v[136:139], v[212:215], v[36:39]
	v_mfma_f32_16x16x32_bf16 v[28:31], v[144:147], v[212:215], v[28:31]
	v_mfma_f32_16x16x32_bf16 v[20:23], v[136:139], v[220:223], v[20:23]
	v_mfma_f32_16x16x32_bf16 v[12:15], v[144:147], v[220:223], v[12:15]
	v_mfma_f32_16x16x32_bf16 v[60:63], v[140:143], v[188:191], v[60:63]
	v_mfma_f32_16x16x32_bf16 v[56:59], v[148:151], v[188:191], v[56:59]
	v_mfma_f32_16x16x32_bf16 v[52:55], v[140:143], v[208:211], v[52:55]
	v_mfma_f32_16x16x32_bf16 v[44:47], v[148:151], v[208:211], v[44:47]
	v_mfma_f32_16x16x32_bf16 v[36:39], v[140:143], v[216:219], v[36:39]
	v_mfma_f32_16x16x32_bf16 v[28:31], v[148:151], v[216:219], v[28:31]
	v_mfma_f32_16x16x32_bf16 v[20:23], v[140:143], v[224:227], v[20:23]
	v_mfma_f32_16x16x32_bf16 v[12:15], v[148:151], v[224:227], v[12:15]
	s_setprio 0
	s_setprio 1
	v_mfma_f32_16x16x32_bf16 v[48:51], v[152:155], v[168:171], v[48:51]
	v_mfma_f32_16x16x32_bf16 v[40:43], v[160:163], v[168:171], v[40:43]
	v_mfma_f32_16x16x32_bf16 v[32:35], v[152:155], v[204:207], v[32:35]
	v_mfma_f32_16x16x32_bf16 v[24:27], v[160:163], v[204:207], v[24:27]
	v_mfma_f32_16x16x32_bf16 v[16:19], v[152:155], v[212:215], v[16:19]
	v_mfma_f32_16x16x32_bf16 v[8:11], v[160:163], v[212:215], v[8:11]
	v_mfma_f32_16x16x32_bf16 v[4:7], v[152:155], v[220:223], v[4:7]
	v_mfma_f32_16x16x32_bf16 v[0:3], v[160:163], v[220:223], v[0:3]
	v_mfma_f32_16x16x32_bf16 v[48:51], v[156:159], v[188:191], v[48:51]
	v_mfma_f32_16x16x32_bf16 v[40:43], v[164:167], v[188:191], v[40:43]
	v_mfma_f32_16x16x32_bf16 v[32:35], v[156:159], v[208:211], v[32:35]
	v_mfma_f32_16x16x32_bf16 v[24:27], v[164:167], v[208:211], v[24:27]
	v_mfma_f32_16x16x32_bf16 v[16:19], v[156:159], v[216:219], v[16:19]
	v_mfma_f32_16x16x32_bf16 v[8:11], v[164:167], v[216:219], v[8:11]
	v_mfma_f32_16x16x32_bf16 v[4:7], v[156:159], v[224:227], v[4:7]
	v_mfma_f32_16x16x32_bf16 v[0:3], v[164:167], v[224:227], v[0:3]
	s_setprio 0
	s_barrier
	s_add_i32 s61, s61, 2
	s_add_u32 s22, s22, 0x100
	s_addc_u32 s23, s23, 0
	s_add_u32 s15, s15, 0x100
	s_addc_u32 s17, s17, 0
	s_cmp_gt_u32 s61, 13
	s_cbranch_scc0 .LBB0_206
	s_and_b64 vcc, exec, s[12:13]
	s_cbranch_vccz .LBB0_209
	s_barrier

.LBB0_589:
	s_add_i32 s68, s20, 2
	s_add_u32 s21, s18, 0xfffa0080
	s_addc_u32 s22, s19, -1
	s_add_i32 s69, 0, 0x10000
	s_cmp_eq_u32 s65, s20
	s_cselect_b32 s23, s15, s22
	s_cselect_b32 s22, s14, s21
	s_cselect_b32 s21, s17, s67
	s_cselect_b32 s20, s16, s66
	s_add_i32 s72, 0, 0x14000
	v_lshl_add_u64 v[174:175], s[18:19], 0, v[172:173]
	s_add_i32 m0, s31, 0xc000
	global_load_lds_dwordx4 v[174:175], off
	v_lshl_add_u64 v[174:175], s[18:19], 0, v[130:131]
	s_add_i32 m0, s31, 0xe000
	s_nop 0
	global_load_lds_dwordx4 v[174:175], off
	v_add_u32_e32 v148, s69, v134
	v_add_u32_e32 v164, s72, v134
	ds_read_b128 v[136:139], v148
	ds_read_b128 v[140:143], v148 offset:1024
	ds_read_b128 v[144:147], v148 offset:2048
	ds_read_b128 v[148:151], v148 offset:3072
	ds_read_b128 v[152:155], v164
	ds_read_b128 v[156:159], v164 offset:1024
	ds_read_b128 v[160:163], v164 offset:2048
	ds_read_b128 v[164:167], v164 offset:3072
	ds_read_b128 v[168:171], v135
	ds_read_b128 v[188:191], v135 offset:1024
	ds_read_b128 v[204:207], v135 offset:2048
	ds_read_b128 v[208:211], v135 offset:3072
	ds_read_b128 v[212:215], v135 offset:4096
	ds_read_b128 v[216:219], v135 offset:5120
	ds_read_b128 v[220:223], v135 offset:6144
	ds_read_b128 v[224:227], v135 offset:7168
	s_waitcnt vmcnt(8)
	s_waitcnt lgkmcnt(0)
	s_barrier
	s_setprio 1
	s_waitcnt lgkmcnt(0)
	v_mfma_f32_16x16x32_bf16 v[124:127], v[136:139], v[168:171], v[124:127]
	v_mfma_f32_16x16x32_bf16 v[120:123], v[144:147], v[168:171], v[120:123]
	v_mfma_f32_16x16x32_bf16 v[116:119], v[136:139], v[204:207], v[116:119]
	v_mfma_f32_16x16x32_bf16 v[108:111], v[144:147], v[204:207], v[108:111]
	v_mfma_f32_16x16x32_bf16 v[100:103], v[136:139], v[212:215], v[100:103]
	v_mfma_f32_16x16x32_bf16 v[92:95], v[144:147], v[212:215], v[92:95]
	v_mfma_f32_16x16x32_bf16 v[84:87], v[136:139], v[220:223], v[84:87]
	v_mfma_f32_16x16x32_bf16 v[76:79], v[144:147], v[220:223], v[76:79]
	v_mfma_f32_16x16x32_bf16 v[124:127], v[140:143], v[188:191], v[124:127]
	v_mfma_f32_16x16x32_bf16 v[120:123], v[148:151], v[188:191], v[120:123]
	v_mfma_f32_16x16x32_bf16 v[116:119], v[140:143], v[208:211], v[116:119]
	v_mfma_f32_16x16x32_bf16 v[108:111], v[148:151], v[208:211], v[108:111]
	v_mfma_f32_16x16x32_bf16 v[100:103], v[140:143], v[216:219], v[100:103]
	v_mfma_f32_16x16x32_bf16 v[92:95], v[148:151], v[216:219], v[92:95]
	v_mfma_f32_16x16x32_bf16 v[84:87], v[140:143], v[224:227], v[84:87]
	v_mfma_f32_16x16x32_bf16 v[76:79], v[148:151], v[224:227], v[76:79]
	s_setprio 0
	s_setprio 1
	v_mfma_f32_16x16x32_bf16 v[112:115], v[152:155], v[168:171], v[112:115]
	v_mfma_f32_16x16x32_bf16 v[104:107], v[160:163], v[168:171], v[104:107]
	v_mfma_f32_16x16x32_bf16 v[96:99], v[152:155], v[204:207], v[96:99]
	v_mfma_f32_16x16x32_bf16 v[88:91], v[160:163], v[204:207], v[88:91]
	v_mfma_f32_16x16x32_bf16 v[80:83], v[152:155], v[212:215], v[80:83]
	v_mfma_f32_16x16x32_bf16 v[72:75], v[160:163], v[212:215], v[72:75]
	v_mfma_f32_16x16x32_bf16 v[68:71], v[152:155], v[220:223], v[68:71]
	v_mfma_f32_16x16x32_bf16 v[64:67], v[160:163], v[220:223], v[64:67]
	v_mfma_f32_16x16x32_bf16 v[112:115], v[156:159], v[188:191], v[112:115]
	v_mfma_f32_16x16x32_bf16 v[104:107], v[164:167], v[188:191], v[104:107]
	v_mfma_f32_16x16x32_bf16 v[96:99], v[156:159], v[208:211], v[96:99]
	v_mfma_f32_16x16x32_bf16 v[88:91], v[164:167], v[208:211], v[88:91]
	v_mfma_f32_16x16x32_bf16 v[80:83], v[156:159], v[216:219], v[80:83]
	v_mfma_f32_16x16x32_bf16 v[72:75], v[164:167], v[216:219], v[72:75]
	v_mfma_f32_16x16x32_bf16 v[68:71], v[156:159], v[224:227], v[68:71]
	v_mfma_f32_16x16x32_bf16 v[64:67], v[164:167], v[224:227], v[64:67]
	s_setprio 0
	s_barrier
	s_add_i32 s69, s69, s30
	v_lshl_add_u64 v[174:175], s[20:21], 0, v[128:129]
	s_mov_b32 m0, s69
	global_load_lds_dwordx4 v[174:175], off
	s_add_i32 m0, s69, 0x2000
	s_add_u32 s70, s20, 0x60000
	v_lshl_add_u64 v[176:177], s[20:21], 0, v[132:133]
	s_addc_u32 s71, s21, 0
	s_add_i32 s69, s72, s30
	global_load_lds_dwordx4 v[176:177], off
	v_lshl_add_u64 v[180:181], s[70:71], 0, v[128:129]
	s_mov_b32 m0, s69
	v_lshl_add_u64 v[182:183], s[22:23], 0, v[130:131]
	global_load_lds_dwordx4 v[180:181], off
	v_lshl_add_u64 v[180:181], s[70:71], 0, v[132:133]
	s_add_i32 m0, s69, 0x2000
	s_nop 0
	global_load_lds_dwordx4 v[180:181], off
	v_lshl_add_u64 v[180:181], s[22:23], 0, v[172:173]
	s_mov_b32 m0, s31
	s_nop 0
	global_load_lds_dwordx4 v[180:181], off
	s_mov_b32 m0, s34
	s_nop 0
	global_load_lds_dwordx4 v[182:183], off
	ds_read_b128 v[168:171], v135 offset:16384
	ds_read_b128 v[188:191], v135 offset:17408
	ds_read_b128 v[204:207], v135 offset:18432
	ds_read_b128 v[208:211], v135 offset:19456
	ds_read_b128 v[212:215], v135 offset:20480
	ds_read_b128 v[216:219], v135 offset:21504
	ds_read_b128 v[220:223], v135 offset:22528
	ds_read_b128 v[224:227], v135 offset:23552
	s_waitcnt vmcnt(8)
	s_waitcnt lgkmcnt(0)
	s_barrier
	s_setprio 1
	s_waitcnt lgkmcnt(0)
	v_mfma_f32_16x16x32_bf16 v[60:63], v[136:139], v[168:171], v[60:63]
	v_mfma_f32_16x16x32_bf16 v[56:59], v[144:147], v[168:171], v[56:59]
	v_mfma_f32_16x16x32_bf16 v[52:55], v[136:139], v[204:207], v[52:55]
	v_mfma_f32_16x16x32_bf16 v[44:47], v[144:147], v[204:207], v[44:47]
	v_mfma_f32_16x16x32_bf16 v[36:39], v[136:139], v[212:215], v[36:39]
	v_mfma_f32_16x16x32_bf16 v[28:31], v[144:147], v[212:215], v[28:31]
	v_mfma_f32_16x16x32_bf16 v[20:23], v[136:139], v[220:223], v[20:23]
	v_mfma_f32_16x16x32_bf16 v[12:15], v[144:147], v[220:223], v[12:15]
	v_mfma_f32_16x16x32_bf16 v[60:63], v[140:143], v[188:191], v[60:63]
	v_mfma_f32_16x16x32_bf16 v[56:59], v[148:151], v[188:191], v[56:59]
	v_mfma_f32_16x16x32_bf16 v[52:55], v[140:143], v[208:211], v[52:55]
	v_mfma_f32_16x16x32_bf16 v[44:47], v[148:151], v[208:211], v[44:47]
	v_mfma_f32_16x16x32_bf16 v[36:39], v[140:143], v[216:219], v[36:39]
	v_mfma_f32_16x16x32_bf16 v[28:31], v[148:151], v[216:219], v[28:31]
	v_mfma_f32_16x16x32_bf16 v[20:23], v[140:143], v[224:227], v[20:23]
	v_mfma_f32_16x16x32_bf16 v[12:15], v[148:151], v[224:227], v[12:15]
	s_setprio 0
	s_setprio 1
	v_mfma_f32_16x16x32_bf16 v[48:51], v[152:155], v[168:171], v[48:51]
	v_mfma_f32_16x16x32_bf16 v[40:43], v[160:163], v[168:171], v[40:43]
	v_mfma_f32_16x16x32_bf16 v[32:35], v[152:155], v[204:207], v[32:35]
	v_mfma_f32_16x16x32_bf16 v[24:27], v[160:163], v[204:207], v[24:27]
	v_mfma_f32_16x16x32_bf16 v[16:19], v[152:155], v[212:215], v[16:19]
	v_mfma_f32_16x16x32_bf16 v[8:11], v[160:163], v[212:215], v[8:11]
	v_mfma_f32_16x16x32_bf16 v[4:7], v[152:155], v[220:223], v[4:7]
	v_mfma_f32_16x16x32_bf16 v[0:3], v[160:163], v[220:223], v[0:3]
	v_mfma_f32_16x16x32_bf16 v[48:51], v[156:159], v[188:191], v[48:51]
	v_mfma_f32_16x16x32_bf16 v[40:43], v[164:167], v[188:191], v[40:43]
	v_mfma_f32_16x16x32_bf16 v[32:35], v[156:159], v[208:211], v[32:35]
	v_mfma_f32_16x16x32_bf16 v[24:27], v[164:167], v[208:211], v[24:27]
	v_mfma_f32_16x16x32_bf16 v[16:19], v[156:159], v[216:219], v[16:19]
	v_mfma_f32_16x16x32_bf16 v[8:11], v[164:167], v[216:219], v[8:11]
	v_mfma_f32_16x16x32_bf16 v[4:7], v[156:159], v[224:227], v[4:7]
	v_mfma_f32_16x16x32_bf16 v[0:3], v[164:167], v[224:227], v[0:3]
	s_setprio 0
	s_barrier
	s_add_i32 s69, 0, 0x18000
	s_add_i32 s70, 0, 0x1c000
	s_add_u32 s22, s22, 0x60000
	s_addc_u32 s23, s23, 0
	s_mov_b32 m0, s35
	v_lshl_add_u64 v[228:229], s[22:23], 0, v[172:173]
	global_load_lds_dwordx4 v[228:229], off
	v_lshl_add_u64 v[228:229], s[22:23], 0, v[130:131]
	s_mov_b32 m0, s36
	s_nop 0
	global_load_lds_dwordx4 v[228:229], off
	v_add_u32_e32 v148, s69, v134
	v_add_u32_e32 v164, s70, v134
	ds_read_b128 v[136:139], v148
	ds_read_b128 v[140:143], v148 offset:1024
	ds_read_b128 v[144:147], v148 offset:2048
	ds_read_b128 v[148:151], v148 offset:3072
	ds_read_b128 v[152:155], v164
	ds_read_b128 v[156:159], v164 offset:1024
	ds_read_b128 v[160:163], v164 offset:2048
	ds_read_b128 v[164:167], v164 offset:3072
	ds_read_b128 v[168:171], v135 offset:32768
	ds_read_b128 v[188:191], v135 offset:33792
	ds_read_b128 v[204:207], v135 offset:34816
	ds_read_b128 v[208:211], v135 offset:35840
	ds_read_b128 v[212:215], v135 offset:36864
	ds_read_b128 v[216:219], v135 offset:37888
	ds_read_b128 v[220:223], v135 offset:38912
	ds_read_b128 v[224:227], v135 offset:39936
	s_waitcnt vmcnt(8)
	s_waitcnt lgkmcnt(0)
	s_barrier
	s_setprio 1
	s_waitcnt lgkmcnt(0)
	v_mfma_f32_16x16x32_bf16 v[124:127], v[136:139], v[168:171], v[124:127]
	v_mfma_f32_16x16x32_bf16 v[120:123], v[144:147], v[168:171], v[120:123]
	v_mfma_f32_16x16x32_bf16 v[116:119], v[136:139], v[204:207], v[116:119]
	v_mfma_f32_16x16x32_bf16 v[108:111], v[144:147], v[204:207], v[108:111]
	v_mfma_f32_16x16x32_bf16 v[100:103], v[136:139], v[212:215], v[100:103]
	v_mfma_f32_16x16x32_bf16 v[92:95], v[144:147], v[212:215], v[92:95]
	v_mfma_f32_16x16x32_bf16 v[84:87], v[136:139], v[220:223], v[84:87]
	v_mfma_f32_16x16x32_bf16 v[76:79], v[144:147], v[220:223], v[76:79]
	v_mfma_f32_16x16x32_bf16 v[124:127], v[140:143], v[188:191], v[124:127]
	v_mfma_f32_16x16x32_bf16 v[120:123], v[148:151], v[188:191], v[120:123]
	v_mfma_f32_16x16x32_bf16 v[116:119], v[140:143], v[208:211], v[116:119]
	v_mfma_f32_16x16x32_bf16 v[108:111], v[148:151], v[208:211], v[108:111]
	v_mfma_f32_16x16x32_bf16 v[100:103], v[140:143], v[216:219], v[100:103]
	v_mfma_f32_16x16x32_bf16 v[92:95], v[148:151], v[216:219], v[92:95]
	v_mfma_f32_16x16x32_bf16 v[84:87], v[140:143], v[224:227], v[84:87]
	v_mfma_f32_16x16x32_bf16 v[76:79], v[148:151], v[224:227], v[76:79]
	s_setprio 0
	s_setprio 1
	v_mfma_f32_16x16x32_bf16 v[112:115], v[152:155], v[168:171], v[112:115]
	v_mfma_f32_16x16x32_bf16 v[104:107], v[160:163], v[168:171], v[104:107]
	v_mfma_f32_16x16x32_bf16 v[96:99], v[152:155], v[204:207], v[96:99]
	v_mfma_f32_16x16x32_bf16 v[88:91], v[160:163], v[204:207], v[88:91]
	v_mfma_f32_16x16x32_bf16 v[80:83], v[152:155], v[212:215], v[80:83]
	v_mfma_f32_16x16x32_bf16 v[72:75], v[160:163], v[212:215], v[72:75]
	v_mfma_f32_16x16x32_bf16 v[68:71], v[152:155], v[220:223], v[68:71]
	v_mfma_f32_16x16x32_bf16 v[64:67], v[160:163], v[220:223], v[64:67]
	v_mfma_f32_16x16x32_bf16 v[112:115], v[156:159], v[188:191], v[112:115]
	v_mfma_f32_16x16x32_bf16 v[104:107], v[164:167], v[188:191], v[104:107]
	v_mfma_f32_16x16x32_bf16 v[96:99], v[156:159], v[208:211], v[96:99]
	v_mfma_f32_16x16x32_bf16 v[88:91], v[164:167], v[208:211], v[88:91]
	v_mfma_f32_16x16x32_bf16 v[80:83], v[156:159], v[216:219], v[80:83]
	v_mfma_f32_16x16x32_bf16 v[72:75], v[164:167], v[216:219], v[72:75]
	v_mfma_f32_16x16x32_bf16 v[68:71], v[156:159], v[224:227], v[68:71]
	v_mfma_f32_16x16x32_bf16 v[64:67], v[164:167], v[224:227], v[64:67]
	s_setprio 0
	s_barrier
	s_add_i32 s22, s69, s30
	v_lshl_add_u64 v[174:175], v[174:175], 0, s[94:95]
	s_mov_b32 m0, s22
	global_load_lds_dwordx4 v[174:175], off
	s_add_i32 m0, s22, 0x2000
	s_add_u32 s20, s20, 0x60080
	v_lshl_add_u64 v[174:175], v[176:177], 0, s[94:95]
	s_addc_u32 s21, s21, 0
	s_add_i32 s22, s70, s30
	global_load_lds_dwordx4 v[174:175], off
	v_lshl_add_u64 v[174:175], s[20:21], 0, v[128:129]
	s_mov_b32 m0, s22
	s_nop 0
	global_load_lds_dwordx4 v[174:175], off
	v_lshl_add_u64 v[174:175], s[20:21], 0, v[132:133]
	s_add_i32 m0, s22, 0x2000
	s_nop 0
	global_load_lds_dwordx4 v[174:175], off
	v_lshl_add_u64 v[174:175], v[180:181], 0, s[94:95]
	s_mov_b32 m0, s45
	s_nop 0
	global_load_lds_dwordx4 v[174:175], off
	v_lshl_add_u64 v[174:175], v[182:183], 0, s[94:95]
	s_mov_b32 m0, s54
	s_nop 0
	global_load_lds_dwordx4 v[174:175], off
	ds_read_b128 v[168:171], v135 offset:49152
	ds_read_b128 v[188:191], v135 offset:50176
	ds_read_b128 v[204:207], v135 offset:51200
	ds_read_b128 v[208:211], v135 offset:52224
	ds_read_b128 v[212:215], v135 offset:53248
	ds_read_b128 v[216:219], v135 offset:54272
	ds_read_b128 v[220:223], v135 offset:55296
	ds_read_b128 v[224:227], v135 offset:56320
	s_waitcnt vmcnt(8)
	s_waitcnt lgkmcnt(0)
	s_barrier
	s_setprio 1
	s_waitcnt lgkmcnt(0)
	v_mfma_f32_16x16x32_bf16 v[60:63], v[136:139], v[168:171], v[60:63]
	v_mfma_f32_16x16x32_bf16 v[56:59], v[144:147], v[168:171], v[56:59]
	v_mfma_f32_16x16x32_bf16 v[52:55], v[136:139], v[204:207], v[52:55]
	v_mfma_f32_16x16x32_bf16 v[44:47], v[144:147], v[204:207], v[44:47]
	v_mfma_f32_16x16x32_bf16 v[36:39], v[136:139], v[212:215], v[36:39]
	v_mfma_f32_16x16x32_bf16 v[28:31], v[144:147], v[212:215], v[28:31]
	v_mfma_f32_16x16x32_bf16 v[20:23], v[136:139], v[220:223], v[20:23]
	v_mfma_f32_16x16x32_bf16 v[12:15], v[144:147], v[220:223], v[12:15]
	v_mfma_f32_16x16x32_bf16 v[60:63], v[140:143], v[188:191], v[60:63]
	v_mfma_f32_16x16x32_bf16 v[56:59], v[148:151], v[188:191], v[56:59]
	v_mfma_f32_16x16x32_bf16 v[52:55], v[140:143], v[208:211], v[52:55]
	v_mfma_f32_16x16x32_bf16 v[44:47], v[148:151], v[208:211], v[44:47]
	v_mfma_f32_16x16x32_bf16 v[36:39], v[140:143], v[216:219], v[36:39]
	v_mfma_f32_16x16x32_bf16 v[28:31], v[148:151], v[216:219], v[28:31]
	v_mfma_f32_16x16x32_bf16 v[20:23], v[140:143], v[224:227], v[20:23]
	v_mfma_f32_16x16x32_bf16 v[12:15], v[148:151], v[224:227], v[12:15]
	s_setprio 0
	s_setprio 1
	v_mfma_f32_16x16x32_bf16 v[48:51], v[152:155], v[168:171], v[48:51]
	v_mfma_f32_16x16x32_bf16 v[40:43], v[160:163], v[168:171], v[40:43]
	v_mfma_f32_16x16x32_bf16 v[32:35], v[152:155], v[204:207], v[32:35]
	v_mfma_f32_16x16x32_bf16 v[24:27], v[160:163], v[204:207], v[24:27]
	v_mfma_f32_16x16x32_bf16 v[16:19], v[152:155], v[212:215], v[16:19]
	v_mfma_f32_16x16x32_bf16 v[8:11], v[160:163], v[212:215], v[8:11]
	v_mfma_f32_16x16x32_bf16 v[4:7], v[152:155], v[220:223], v[4:7]
	v_mfma_f32_16x16x32_bf16 v[0:3], v[160:163], v[220:223], v[0:3]
	v_mfma_f32_16x16x32_bf16 v[48:51], v[156:159], v[188:191], v[48:51]
	v_mfma_f32_16x16x32_bf16 v[40:43], v[164:167], v[188:191], v[40:43]
	v_mfma_f32_16x16x32_bf16 v[32:35], v[156:159], v[208:211], v[32:35]
	v_mfma_f32_16x16x32_bf16 v[24:27], v[164:167], v[208:211], v[24:27]
	v_mfma_f32_16x16x32_bf16 v[16:19], v[156:159], v[216:219], v[16:19]
	v_mfma_f32_16x16x32_bf16 v[8:11], v[164:167], v[216:219], v[8:11]
	v_mfma_f32_16x16x32_bf16 v[4:7], v[156:159], v[224:227], v[4:7]
	v_mfma_f32_16x16x32_bf16 v[0:3], v[164:167], v[224:227], v[0:3]
	s_setprio 0
	s_barrier
	s_add_u32 s18, s18, 0x100
	s_addc_u32 s19, s19, 0
	s_add_u32 s66, s66, 0x100
	s_addc_u32 s67, s67, 0
	s_cmp_ge_i32 s68, s62
	s_mov_b32 s20, s68
	s_cbranch_scc0 .LBB0_589
	s_and_b64 vcc, exec, s[10:11]
	s_cbranch_vccz .LBB0_592
	s_barrier

.LBB0_671:
	s_add_u32 s36, s34, 0xfffc0080
	s_addc_u32 s37, s35, -1
	s_add_i32 s87, 0, 0x10000
	s_cmp_eq_u32 s85, 12
	s_cselect_b32 s39, s29, s37
	s_cselect_b32 s38, s28, s36
	s_cselect_b32 s37, s31, s9
	s_cselect_b32 s36, s30, s7
	s_add_i32 s93, 0, 0x14000
	v_lshl_add_u64 v[174:175], s[34:35], 0, v[172:173]
	s_add_i32 m0, s62, 0xc000
	global_load_lds_dwordx4 v[174:175], off
	v_lshl_add_u64 v[174:175], s[34:35], 0, v[132:133]
	s_add_i32 m0, s62, 0xe000
	s_nop 0
	global_load_lds_dwordx4 v[174:175], off
	v_add_u32_e32 v148, s87, v134
	v_add_u32_e32 v164, s93, v134
	ds_read_b128 v[136:139], v148
	ds_read_b128 v[140:143], v148 offset:1024
	ds_read_b128 v[144:147], v148 offset:2048
	ds_read_b128 v[148:151], v148 offset:3072
	ds_read_b128 v[152:155], v164
	ds_read_b128 v[156:159], v164 offset:1024
	ds_read_b128 v[160:163], v164 offset:2048
	ds_read_b128 v[164:167], v164 offset:3072
	ds_read_b128 v[168:171], v135
	ds_read_b128 v[188:191], v135 offset:1024
	ds_read_b128 v[204:207], v135 offset:2048
	ds_read_b128 v[208:211], v135 offset:3072
	ds_read_b128 v[212:215], v135 offset:4096
	ds_read_b128 v[216:219], v135 offset:5120
	ds_read_b128 v[220:223], v135 offset:6144
	ds_read_b128 v[224:227], v135 offset:7168
	s_waitcnt vmcnt(8)
	s_waitcnt lgkmcnt(0)
	s_barrier
	s_setprio 1
	s_waitcnt lgkmcnt(0)
	v_mfma_f32_16x16x32_bf16 v[124:127], v[136:139], v[168:171], v[124:127]
	v_mfma_f32_16x16x32_bf16 v[120:123], v[144:147], v[168:171], v[120:123]
	v_mfma_f32_16x16x32_bf16 v[112:115], v[136:139], v[204:207], v[112:115]
	v_mfma_f32_16x16x32_bf16 v[104:107], v[144:147], v[204:207], v[104:107]
	v_mfma_f32_16x16x32_bf16 v[96:99], v[136:139], v[212:215], v[96:99]
	v_mfma_f32_16x16x32_bf16 v[88:91], v[144:147], v[212:215], v[88:91]
	v_mfma_f32_16x16x32_bf16 v[80:83], v[136:139], v[220:223], v[80:83]
	v_mfma_f32_16x16x32_bf16 v[72:75], v[144:147], v[220:223], v[72:75]
	v_mfma_f32_16x16x32_bf16 v[124:127], v[140:143], v[188:191], v[124:127]
	v_mfma_f32_16x16x32_bf16 v[120:123], v[148:151], v[188:191], v[120:123]
	v_mfma_f32_16x16x32_bf16 v[112:115], v[140:143], v[208:211], v[112:115]
	v_mfma_f32_16x16x32_bf16 v[104:107], v[148:151], v[208:211], v[104:107]
	v_mfma_f32_16x16x32_bf16 v[96:99], v[140:143], v[216:219], v[96:99]
	v_mfma_f32_16x16x32_bf16 v[88:91], v[148:151], v[216:219], v[88:91]
	v_mfma_f32_16x16x32_bf16 v[80:83], v[140:143], v[224:227], v[80:83]
	v_mfma_f32_16x16x32_bf16 v[72:75], v[148:151], v[224:227], v[72:75]
	s_setprio 0
	s_setprio 1
	v_mfma_f32_16x16x32_bf16 v[116:119], v[152:155], v[168:171], v[116:119]
	v_mfma_f32_16x16x32_bf16 v[108:111], v[160:163], v[168:171], v[108:111]
	v_mfma_f32_16x16x32_bf16 v[100:103], v[152:155], v[204:207], v[100:103]
	v_mfma_f32_16x16x32_bf16 v[92:95], v[160:163], v[204:207], v[92:95]
	v_mfma_f32_16x16x32_bf16 v[84:87], v[152:155], v[212:215], v[84:87]
	v_mfma_f32_16x16x32_bf16 v[76:79], v[160:163], v[212:215], v[76:79]
	v_mfma_f32_16x16x32_bf16 v[68:71], v[152:155], v[220:223], v[68:71]
	v_mfma_f32_16x16x32_bf16 v[64:67], v[160:163], v[220:223], v[64:67]
	v_mfma_f32_16x16x32_bf16 v[116:119], v[156:159], v[188:191], v[116:119]
	v_mfma_f32_16x16x32_bf16 v[108:111], v[164:167], v[188:191], v[108:111]
	v_mfma_f32_16x16x32_bf16 v[100:103], v[156:159], v[208:211], v[100:103]
	v_mfma_f32_16x16x32_bf16 v[92:95], v[164:167], v[208:211], v[92:95]
	v_mfma_f32_16x16x32_bf16 v[84:87], v[156:159], v[216:219], v[84:87]
	v_mfma_f32_16x16x32_bf16 v[76:79], v[164:167], v[216:219], v[76:79]
	v_mfma_f32_16x16x32_bf16 v[68:71], v[156:159], v[224:227], v[68:71]
	v_mfma_f32_16x16x32_bf16 v[64:67], v[164:167], v[224:227], v[64:67]
	s_setprio 0
	s_barrier
	s_add_i32 s87, s87, s61
	v_lshl_add_u64 v[174:175], s[36:37], 0, v[128:129]
	s_mov_b32 m0, s87
	global_load_lds_dwordx4 v[174:175], off
	s_add_i32 m0, s87, 0x2000
	s_add_u32 s88, s36, 0x40000
	v_lshl_add_u64 v[176:177], s[36:37], 0, v[130:131]
	s_addc_u32 s89, s37, 0
	s_add_i32 s87, s93, s61
	global_load_lds_dwordx4 v[176:177], off
	v_lshl_add_u64 v[180:181], s[88:89], 0, v[128:129]
	s_mov_b32 m0, s87
	v_lshl_add_u64 v[182:183], s[38:39], 0, v[132:133]
	global_load_lds_dwordx4 v[180:181], off
	v_lshl_add_u64 v[180:181], s[88:89], 0, v[130:131]
	s_add_i32 m0, s87, 0x2000
	s_nop 0
	global_load_lds_dwordx4 v[180:181], off
	v_lshl_add_u64 v[180:181], s[38:39], 0, v[172:173]
	s_mov_b32 m0, s62
	s_nop 0
	global_load_lds_dwordx4 v[180:181], off
	s_mov_b32 m0, s63
	s_nop 0
	global_load_lds_dwordx4 v[182:183], off
	ds_read_b128 v[168:171], v135 offset:16384
	ds_read_b128 v[188:191], v135 offset:17408
	ds_read_b128 v[204:207], v135 offset:18432
	ds_read_b128 v[208:211], v135 offset:19456
	ds_read_b128 v[212:215], v135 offset:20480
	ds_read_b128 v[216:219], v135 offset:21504
	ds_read_b128 v[220:223], v135 offset:22528
	ds_read_b128 v[224:227], v135 offset:23552
	s_waitcnt vmcnt(8)
	s_waitcnt lgkmcnt(0)
	s_barrier
	s_setprio 1
	s_waitcnt lgkmcnt(0)
	v_mfma_f32_16x16x32_bf16 v[60:63], v[136:139], v[168:171], v[60:63]
	v_mfma_f32_16x16x32_bf16 v[56:59], v[144:147], v[168:171], v[56:59]
	v_mfma_f32_16x16x32_bf16 v[48:51], v[136:139], v[204:207], v[48:51]
	v_mfma_f32_16x16x32_bf16 v[40:43], v[144:147], v[204:207], v[40:43]
	v_mfma_f32_16x16x32_bf16 v[32:35], v[136:139], v[212:215], v[32:35]
	v_mfma_f32_16x16x32_bf16 v[24:27], v[144:147], v[212:215], v[24:27]
	v_mfma_f32_16x16x32_bf16 v[16:19], v[136:139], v[220:223], v[16:19]
	v_mfma_f32_16x16x32_bf16 v[8:11], v[144:147], v[220:223], v[8:11]
	v_mfma_f32_16x16x32_bf16 v[60:63], v[140:143], v[188:191], v[60:63]
	v_mfma_f32_16x16x32_bf16 v[56:59], v[148:151], v[188:191], v[56:59]
	v_mfma_f32_16x16x32_bf16 v[48:51], v[140:143], v[208:211], v[48:51]
	v_mfma_f32_16x16x32_bf16 v[40:43], v[148:151], v[208:211], v[40:43]
	v_mfma_f32_16x16x32_bf16 v[32:35], v[140:143], v[216:219], v[32:35]
	v_mfma_f32_16x16x32_bf16 v[24:27], v[148:151], v[216:219], v[24:27]
	v_mfma_f32_16x16x32_bf16 v[16:19], v[140:143], v[224:227], v[16:19]
	v_mfma_f32_16x16x32_bf16 v[8:11], v[148:151], v[224:227], v[8:11]
	s_setprio 0
	s_setprio 1
	v_mfma_f32_16x16x32_bf16 v[52:55], v[152:155], v[168:171], v[52:55]
	v_mfma_f32_16x16x32_bf16 v[44:47], v[160:163], v[168:171], v[44:47]
	v_mfma_f32_16x16x32_bf16 v[36:39], v[152:155], v[204:207], v[36:39]
	v_mfma_f32_16x16x32_bf16 v[28:31], v[160:163], v[204:207], v[28:31]
	v_mfma_f32_16x16x32_bf16 v[20:23], v[152:155], v[212:215], v[20:23]
	v_mfma_f32_16x16x32_bf16 v[12:15], v[160:163], v[212:215], v[12:15]
	v_mfma_f32_16x16x32_bf16 v[4:7], v[152:155], v[220:223], v[4:7]
	v_mfma_f32_16x16x32_bf16 v[0:3], v[160:163], v[220:223], v[0:3]
	v_mfma_f32_16x16x32_bf16 v[52:55], v[156:159], v[188:191], v[52:55]
	v_mfma_f32_16x16x32_bf16 v[44:47], v[164:167], v[188:191], v[44:47]
	v_mfma_f32_16x16x32_bf16 v[36:39], v[156:159], v[208:211], v[36:39]
	v_mfma_f32_16x16x32_bf16 v[28:31], v[164:167], v[208:211], v[28:31]
	v_mfma_f32_16x16x32_bf16 v[20:23], v[156:159], v[216:219], v[20:23]
	v_mfma_f32_16x16x32_bf16 v[12:15], v[164:167], v[216:219], v[12:15]
	v_mfma_f32_16x16x32_bf16 v[4:7], v[156:159], v[224:227], v[4:7]
	v_mfma_f32_16x16x32_bf16 v[0:3], v[164:167], v[224:227], v[0:3]
	s_setprio 0
	s_barrier
	s_add_i32 s87, 0, 0x18000
	s_add_i32 s88, 0, 0x1c000
	s_add_u32 s38, s38, 0x40000
	s_addc_u32 s39, s39, 0
	s_mov_b32 m0, s64
	v_lshl_add_u64 v[228:229], s[38:39], 0, v[172:173]
	global_load_lds_dwordx4 v[228:229], off
	v_lshl_add_u64 v[228:229], s[38:39], 0, v[132:133]
	s_mov_b32 m0, s65
	s_nop 0
	global_load_lds_dwordx4 v[228:229], off
	v_add_u32_e32 v148, s87, v134
	v_add_u32_e32 v164, s88, v134
	ds_read_b128 v[136:139], v148
	ds_read_b128 v[140:143], v148 offset:1024
	ds_read_b128 v[144:147], v148 offset:2048
	ds_read_b128 v[148:151], v148 offset:3072
	ds_read_b128 v[152:155], v164
	ds_read_b128 v[156:159], v164 offset:1024
	ds_read_b128 v[160:163], v164 offset:2048
	ds_read_b128 v[164:167], v164 offset:3072
	ds_read_b128 v[168:171], v135 offset:32768
	ds_read_b128 v[188:191], v135 offset:33792
	ds_read_b128 v[204:207], v135 offset:34816
	ds_read_b128 v[208:211], v135 offset:35840
	ds_read_b128 v[212:215], v135 offset:36864
	ds_read_b128 v[216:219], v135 offset:37888
	ds_read_b128 v[220:223], v135 offset:38912
	ds_read_b128 v[224:227], v135 offset:39936
	s_waitcnt vmcnt(8)
	s_waitcnt lgkmcnt(0)
	s_barrier
	s_setprio 1
	s_waitcnt lgkmcnt(0)
	v_mfma_f32_16x16x32_bf16 v[124:127], v[136:139], v[168:171], v[124:127]
	v_mfma_f32_16x16x32_bf16 v[120:123], v[144:147], v[168:171], v[120:123]
	v_mfma_f32_16x16x32_bf16 v[112:115], v[136:139], v[204:207], v[112:115]
	v_mfma_f32_16x16x32_bf16 v[104:107], v[144:147], v[204:207], v[104:107]
	v_mfma_f32_16x16x32_bf16 v[96:99], v[136:139], v[212:215], v[96:99]
	v_mfma_f32_16x16x32_bf16 v[88:91], v[144:147], v[212:215], v[88:91]
	v_mfma_f32_16x16x32_bf16 v[80:83], v[136:139], v[220:223], v[80:83]
	v_mfma_f32_16x16x32_bf16 v[72:75], v[144:147], v[220:223], v[72:75]
	v_mfma_f32_16x16x32_bf16 v[124:127], v[140:143], v[188:191], v[124:127]
	v_mfma_f32_16x16x32_bf16 v[120:123], v[148:151], v[188:191], v[120:123]
	v_mfma_f32_16x16x32_bf16 v[112:115], v[140:143], v[208:211], v[112:115]
	v_mfma_f32_16x16x32_bf16 v[104:107], v[148:151], v[208:211], v[104:107]
	v_mfma_f32_16x16x32_bf16 v[96:99], v[140:143], v[216:219], v[96:99]
	v_mfma_f32_16x16x32_bf16 v[88:91], v[148:151], v[216:219], v[88:91]
	v_mfma_f32_16x16x32_bf16 v[80:83], v[140:143], v[224:227], v[80:83]
	v_mfma_f32_16x16x32_bf16 v[72:75], v[148:151], v[224:227], v[72:75]
	s_setprio 0
	s_setprio 1
	v_mfma_f32_16x16x32_bf16 v[116:119], v[152:155], v[168:171], v[116:119]
	v_mfma_f32_16x16x32_bf16 v[108:111], v[160:163], v[168:171], v[108:111]
	v_mfma_f32_16x16x32_bf16 v[100:103], v[152:155], v[204:207], v[100:103]
	v_mfma_f32_16x16x32_bf16 v[92:95], v[160:163], v[204:207], v[92:95]
	v_mfma_f32_16x16x32_bf16 v[84:87], v[152:155], v[212:215], v[84:87]
	v_mfma_f32_16x16x32_bf16 v[76:79], v[160:163], v[212:215], v[76:79]
	v_mfma_f32_16x16x32_bf16 v[68:71], v[152:155], v[220:223], v[68:71]
	v_mfma_f32_16x16x32_bf16 v[64:67], v[160:163], v[220:223], v[64:67]
	v_mfma_f32_16x16x32_bf16 v[116:119], v[156:159], v[188:191], v[116:119]
	v_mfma_f32_16x16x32_bf16 v[108:111], v[164:167], v[188:191], v[108:111]
	v_mfma_f32_16x16x32_bf16 v[100:103], v[156:159], v[208:211], v[100:103]
	v_mfma_f32_16x16x32_bf16 v[92:95], v[164:167], v[208:211], v[92:95]
	v_mfma_f32_16x16x32_bf16 v[84:87], v[156:159], v[216:219], v[84:87]
	v_mfma_f32_16x16x32_bf16 v[76:79], v[164:167], v[216:219], v[76:79]
	v_mfma_f32_16x16x32_bf16 v[68:71], v[156:159], v[224:227], v[68:71]
	v_mfma_f32_16x16x32_bf16 v[64:67], v[164:167], v[224:227], v[64:67]
	s_setprio 0
	s_barrier
	s_add_i32 s38, s87, s61
	v_lshl_add_u64 v[174:175], v[174:175], 0, s[94:95]
	s_mov_b32 m0, s38
	global_load_lds_dwordx4 v[174:175], off
	s_add_i32 m0, s38, 0x2000
	s_add_u32 s36, s36, 0x40080
	v_lshl_add_u64 v[174:175], v[176:177], 0, s[94:95]
	s_addc_u32 s37, s37, 0
	s_add_i32 s38, s88, s61
	global_load_lds_dwordx4 v[174:175], off
	v_lshl_add_u64 v[174:175], s[36:37], 0, v[128:129]
	s_mov_b32 m0, s38
	s_nop 0
	global_load_lds_dwordx4 v[174:175], off
	v_lshl_add_u64 v[174:175], s[36:37], 0, v[130:131]
	s_add_i32 m0, s38, 0x2000
	s_nop 0
	global_load_lds_dwordx4 v[174:175], off
	v_lshl_add_u64 v[174:175], v[180:181], 0, s[94:95]
	s_mov_b32 m0, s70
	s_nop 0
	global_load_lds_dwordx4 v[174:175], off
	v_lshl_add_u64 v[174:175], v[182:183], 0, s[94:95]
	s_mov_b32 m0, s71
	s_nop 0
	global_load_lds_dwordx4 v[174:175], off
	ds_read_b128 v[168:171], v135 offset:49152
	ds_read_b128 v[188:191], v135 offset:50176
	ds_read_b128 v[204:207], v135 offset:51200
	ds_read_b128 v[208:211], v135 offset:52224
	ds_read_b128 v[212:215], v135 offset:53248
	ds_read_b128 v[216:219], v135 offset:54272
	ds_read_b128 v[220:223], v135 offset:55296
	ds_read_b128 v[224:227], v135 offset:56320
	s_waitcnt vmcnt(8)
	s_waitcnt lgkmcnt(0)
	s_barrier
	s_setprio 1
	s_waitcnt lgkmcnt(0)
	v_mfma_f32_16x16x32_bf16 v[60:63], v[136:139], v[168:171], v[60:63]
	v_mfma_f32_16x16x32_bf16 v[56:59], v[144:147], v[168:171], v[56:59]
	v_mfma_f32_16x16x32_bf16 v[48:51], v[136:139], v[204:207], v[48:51]
	v_mfma_f32_16x16x32_bf16 v[40:43], v[144:147], v[204:207], v[40:43]
	v_mfma_f32_16x16x32_bf16 v[32:35], v[136:139], v[212:215], v[32:35]
	v_mfma_f32_16x16x32_bf16 v[24:27], v[144:147], v[212:215], v[24:27]
	v_mfma_f32_16x16x32_bf16 v[16:19], v[136:139], v[220:223], v[16:19]
	v_mfma_f32_16x16x32_bf16 v[8:11], v[144:147], v[220:223], v[8:11]
	v_mfma_f32_16x16x32_bf16 v[60:63], v[140:143], v[188:191], v[60:63]
	v_mfma_f32_16x16x32_bf16 v[56:59], v[148:151], v[188:191], v[56:59]
	v_mfma_f32_16x16x32_bf16 v[48:51], v[140:143], v[208:211], v[48:51]
	v_mfma_f32_16x16x32_bf16 v[40:43], v[148:151], v[208:211], v[40:43]
	v_mfma_f32_16x16x32_bf16 v[32:35], v[140:143], v[216:219], v[32:35]
	v_mfma_f32_16x16x32_bf16 v[24:27], v[148:151], v[216:219], v[24:27]
	v_mfma_f32_16x16x32_bf16 v[16:19], v[140:143], v[224:227], v[16:19]
	v_mfma_f32_16x16x32_bf16 v[8:11], v[148:151], v[224:227], v[8:11]
	s_setprio 0
	s_setprio 1
	v_mfma_f32_16x16x32_bf16 v[52:55], v[152:155], v[168:171], v[52:55]
	v_mfma_f32_16x16x32_bf16 v[44:47], v[160:163], v[168:171], v[44:47]
	v_mfma_f32_16x16x32_bf16 v[36:39], v[152:155], v[204:207], v[36:39]
	v_mfma_f32_16x16x32_bf16 v[28:31], v[160:163], v[204:207], v[28:31]
	v_mfma_f32_16x16x32_bf16 v[20:23], v[152:155], v[212:215], v[20:23]
	v_mfma_f32_16x16x32_bf16 v[12:15], v[160:163], v[212:215], v[12:15]
	v_mfma_f32_16x16x32_bf16 v[4:7], v[152:155], v[220:223], v[4:7]
	v_mfma_f32_16x16x32_bf16 v[0:3], v[160:163], v[220:223], v[0:3]
	v_mfma_f32_16x16x32_bf16 v[52:55], v[156:159], v[188:191], v[52:55]
	v_mfma_f32_16x16x32_bf16 v[44:47], v[164:167], v[188:191], v[44:47]
	v_mfma_f32_16x16x32_bf16 v[36:39], v[156:159], v[208:211], v[36:39]
	v_mfma_f32_16x16x32_bf16 v[28:31], v[164:167], v[208:211], v[28:31]
	v_mfma_f32_16x16x32_bf16 v[20:23], v[156:159], v[216:219], v[20:23]
	v_mfma_f32_16x16x32_bf16 v[12:15], v[164:167], v[216:219], v[12:15]
	v_mfma_f32_16x16x32_bf16 v[4:7], v[156:159], v[224:227], v[4:7]
	v_mfma_f32_16x16x32_bf16 v[0:3], v[164:167], v[224:227], v[0:3]
	s_setprio 0
	s_barrier
	s_add_i32 s85, s85, 2
	s_add_u32 s34, s34, 0x100
	s_addc_u32 s35, s35, 0
	s_add_u32 s7, s7, 0x100
	s_addc_u32 s9, s9, 0
	s_cmp_gt_u32 s85, 13
	s_cbranch_scc0 .LBB0_671
	s_and_b64 vcc, exec, s[26:27]
	s_cbranch_vccz .LBB0_674
	s_barrier

.LBB0_747:
	s_add_u32 s24, s22, 0xfffc0080
	s_addc_u32 s25, s23, -1
	s_add_i32 s62, 0, 0x10000
	s_cmp_eq_u32 s61, 12
	s_cselect_b32 s27, s19, s25
	s_cselect_b32 s26, s18, s24
	s_cselect_b32 s25, s21, s17
	s_cselect_b32 s24, s20, s15
	s_add_i32 s64, 0, 0x14000
	v_lshl_add_u64 v[174:175], s[22:23], 0, v[172:173]
	s_add_i32 m0, s34, 0xc000
	global_load_lds_dwordx4 v[174:175], off
	v_lshl_add_u64 v[174:175], s[22:23], 0, v[130:131]
	s_add_i32 m0, s34, 0xe000
	s_nop 0
	global_load_lds_dwordx4 v[174:175], off
	v_add_u32_e32 v148, s62, v134
	v_add_u32_e32 v164, s64, v134
	ds_read_b128 v[136:139], v148
	ds_read_b128 v[140:143], v148 offset:1024
	ds_read_b128 v[144:147], v148 offset:2048
	ds_read_b128 v[148:151], v148 offset:3072
	ds_read_b128 v[152:155], v164
	ds_read_b128 v[156:159], v164 offset:1024
	ds_read_b128 v[160:163], v164 offset:2048
	ds_read_b128 v[164:167], v164 offset:3072
	ds_read_b128 v[168:171], v135
	ds_read_b128 v[188:191], v135 offset:1024
	ds_read_b128 v[204:207], v135 offset:2048
	ds_read_b128 v[208:211], v135 offset:3072
	ds_read_b128 v[212:215], v135 offset:4096
	ds_read_b128 v[216:219], v135 offset:5120
	ds_read_b128 v[220:223], v135 offset:6144
	ds_read_b128 v[224:227], v135 offset:7168
	s_waitcnt vmcnt(8)
	s_waitcnt lgkmcnt(0)
	s_barrier
	s_setprio 1
	s_waitcnt lgkmcnt(0)
	v_mfma_f32_16x16x32_bf16 v[124:127], v[136:139], v[168:171], v[124:127]
	v_mfma_f32_16x16x32_bf16 v[120:123], v[144:147], v[168:171], v[120:123]
	v_mfma_f32_16x16x32_bf16 v[112:115], v[136:139], v[204:207], v[112:115]
	v_mfma_f32_16x16x32_bf16 v[104:107], v[144:147], v[204:207], v[104:107]
	v_mfma_f32_16x16x32_bf16 v[96:99], v[136:139], v[212:215], v[96:99]
	v_mfma_f32_16x16x32_bf16 v[88:91], v[144:147], v[212:215], v[88:91]
	v_mfma_f32_16x16x32_bf16 v[80:83], v[136:139], v[220:223], v[80:83]
	v_mfma_f32_16x16x32_bf16 v[72:75], v[144:147], v[220:223], v[72:75]
	v_mfma_f32_16x16x32_bf16 v[124:127], v[140:143], v[188:191], v[124:127]
	v_mfma_f32_16x16x32_bf16 v[120:123], v[148:151], v[188:191], v[120:123]
	v_mfma_f32_16x16x32_bf16 v[112:115], v[140:143], v[208:211], v[112:115]
	v_mfma_f32_16x16x32_bf16 v[104:107], v[148:151], v[208:211], v[104:107]
	v_mfma_f32_16x16x32_bf16 v[96:99], v[140:143], v[216:219], v[96:99]
	v_mfma_f32_16x16x32_bf16 v[88:91], v[148:151], v[216:219], v[88:91]
	v_mfma_f32_16x16x32_bf16 v[80:83], v[140:143], v[224:227], v[80:83]
	v_mfma_f32_16x16x32_bf16 v[72:75], v[148:151], v[224:227], v[72:75]
	s_setprio 0
	s_setprio 1
	v_mfma_f32_16x16x32_bf16 v[116:119], v[152:155], v[168:171], v[116:119]
	v_mfma_f32_16x16x32_bf16 v[108:111], v[160:163], v[168:171], v[108:111]
	v_mfma_f32_16x16x32_bf16 v[100:103], v[152:155], v[204:207], v[100:103]
	v_mfma_f32_16x16x32_bf16 v[92:95], v[160:163], v[204:207], v[92:95]
	v_mfma_f32_16x16x32_bf16 v[84:87], v[152:155], v[212:215], v[84:87]
	v_mfma_f32_16x16x32_bf16 v[76:79], v[160:163], v[212:215], v[76:79]
	v_mfma_f32_16x16x32_bf16 v[68:71], v[152:155], v[220:223], v[68:71]
	v_mfma_f32_16x16x32_bf16 v[64:67], v[160:163], v[220:223], v[64:67]
	v_mfma_f32_16x16x32_bf16 v[116:119], v[156:159], v[188:191], v[116:119]
	v_mfma_f32_16x16x32_bf16 v[108:111], v[164:167], v[188:191], v[108:111]
	v_mfma_f32_16x16x32_bf16 v[100:103], v[156:159], v[208:211], v[100:103]
	v_mfma_f32_16x16x32_bf16 v[92:95], v[164:167], v[208:211], v[92:95]
	v_mfma_f32_16x16x32_bf16 v[84:87], v[156:159], v[216:219], v[84:87]
	v_mfma_f32_16x16x32_bf16 v[76:79], v[164:167], v[216:219], v[76:79]
	v_mfma_f32_16x16x32_bf16 v[68:71], v[156:159], v[224:227], v[68:71]
	v_mfma_f32_16x16x32_bf16 v[64:67], v[164:167], v[224:227], v[64:67]
	s_setprio 0
	s_barrier
	s_add_i32 s62, s62, s31
	v_lshl_add_u64 v[174:175], s[24:25], 0, v[128:129]
	s_mov_b32 m0, s62
	global_load_lds_dwordx4 v[174:175], off
	s_add_i32 m0, s62, 0x2000
	s_add_u32 s62, s24, 0x40000
	v_lshl_add_u64 v[176:177], s[24:25], 0, v[132:133]
	s_addc_u32 s63, s25, 0
	s_add_i32 s64, s64, s31
	global_load_lds_dwordx4 v[176:177], off
	v_lshl_add_u64 v[180:181], s[62:63], 0, v[128:129]
	s_mov_b32 m0, s64
	v_lshl_add_u64 v[182:183], s[26:27], 0, v[130:131]
	global_load_lds_dwordx4 v[180:181], off
	v_lshl_add_u64 v[180:181], s[62:63], 0, v[132:133]
	s_add_i32 m0, s64, 0x2000
	s_nop 0
	global_load_lds_dwordx4 v[180:181], off
	v_lshl_add_u64 v[180:181], s[26:27], 0, v[172:173]
	s_mov_b32 m0, s34
	s_nop 0
	global_load_lds_dwordx4 v[180:181], off
	s_mov_b32 m0, s35
	s_nop 0
	global_load_lds_dwordx4 v[182:183], off
	ds_read_b128 v[168:171], v135 offset:16384
	ds_read_b128 v[188:191], v135 offset:17408
	ds_read_b128 v[204:207], v135 offset:18432
	ds_read_b128 v[208:211], v135 offset:19456
	ds_read_b128 v[212:215], v135 offset:20480
	ds_read_b128 v[216:219], v135 offset:21504
	ds_read_b128 v[220:223], v135 offset:22528
	ds_read_b128 v[224:227], v135 offset:23552
	s_waitcnt vmcnt(8)
	s_waitcnt lgkmcnt(0)
	s_barrier
	s_setprio 1
	s_waitcnt lgkmcnt(0)
	v_mfma_f32_16x16x32_bf16 v[60:63], v[136:139], v[168:171], v[60:63]
	v_mfma_f32_16x16x32_bf16 v[56:59], v[144:147], v[168:171], v[56:59]
	v_mfma_f32_16x16x32_bf16 v[48:51], v[136:139], v[204:207], v[48:51]
	v_mfma_f32_16x16x32_bf16 v[40:43], v[144:147], v[204:207], v[40:43]
	v_mfma_f32_16x16x32_bf16 v[32:35], v[136:139], v[212:215], v[32:35]
	v_mfma_f32_16x16x32_bf16 v[24:27], v[144:147], v[212:215], v[24:27]
	v_mfma_f32_16x16x32_bf16 v[16:19], v[136:139], v[220:223], v[16:19]
	v_mfma_f32_16x16x32_bf16 v[8:11], v[144:147], v[220:223], v[8:11]
	v_mfma_f32_16x16x32_bf16 v[60:63], v[140:143], v[188:191], v[60:63]
	v_mfma_f32_16x16x32_bf16 v[56:59], v[148:151], v[188:191], v[56:59]
	v_mfma_f32_16x16x32_bf16 v[48:51], v[140:143], v[208:211], v[48:51]
	v_mfma_f32_16x16x32_bf16 v[40:43], v[148:151], v[208:211], v[40:43]
	v_mfma_f32_16x16x32_bf16 v[32:35], v[140:143], v[216:219], v[32:35]
	v_mfma_f32_16x16x32_bf16 v[24:27], v[148:151], v[216:219], v[24:27]
	v_mfma_f32_16x16x32_bf16 v[16:19], v[140:143], v[224:227], v[16:19]
	v_mfma_f32_16x16x32_bf16 v[8:11], v[148:151], v[224:227], v[8:11]
	s_setprio 0
	s_setprio 1
	v_mfma_f32_16x16x32_bf16 v[52:55], v[152:155], v[168:171], v[52:55]
	v_mfma_f32_16x16x32_bf16 v[44:47], v[160:163], v[168:171], v[44:47]
	v_mfma_f32_16x16x32_bf16 v[36:39], v[152:155], v[204:207], v[36:39]
	v_mfma_f32_16x16x32_bf16 v[28:31], v[160:163], v[204:207], v[28:31]
	v_mfma_f32_16x16x32_bf16 v[20:23], v[152:155], v[212:215], v[20:23]
	v_mfma_f32_16x16x32_bf16 v[12:15], v[160:163], v[212:215], v[12:15]
	v_mfma_f32_16x16x32_bf16 v[4:7], v[152:155], v[220:223], v[4:7]
	v_mfma_f32_16x16x32_bf16 v[0:3], v[160:163], v[220:223], v[0:3]
	v_mfma_f32_16x16x32_bf16 v[52:55], v[156:159], v[188:191], v[52:55]
	v_mfma_f32_16x16x32_bf16 v[44:47], v[164:167], v[188:191], v[44:47]
	v_mfma_f32_16x16x32_bf16 v[36:39], v[156:159], v[208:211], v[36:39]
	v_mfma_f32_16x16x32_bf16 v[28:31], v[164:167], v[208:211], v[28:31]
	v_mfma_f32_16x16x32_bf16 v[20:23], v[156:159], v[216:219], v[20:23]
	v_mfma_f32_16x16x32_bf16 v[12:15], v[164:167], v[216:219], v[12:15]
	v_mfma_f32_16x16x32_bf16 v[4:7], v[156:159], v[224:227], v[4:7]
	v_mfma_f32_16x16x32_bf16 v[0:3], v[164:167], v[224:227], v[0:3]
	s_setprio 0
	s_barrier
	s_add_i32 s62, 0, 0x18000
	s_add_i32 s63, 0, 0x1c000
	s_add_u32 s26, s26, 0x40000
	s_addc_u32 s27, s27, 0
	s_mov_b32 m0, s36
	v_lshl_add_u64 v[228:229], s[26:27], 0, v[172:173]
	global_load_lds_dwordx4 v[228:229], off
	v_lshl_add_u64 v[228:229], s[26:27], 0, v[130:131]
	s_mov_b32 m0, s37
	s_nop 0
	global_load_lds_dwordx4 v[228:229], off
	v_add_u32_e32 v148, s62, v134
	v_add_u32_e32 v164, s63, v134
	ds_read_b128 v[136:139], v148
	ds_read_b128 v[140:143], v148 offset:1024
	ds_read_b128 v[144:147], v148 offset:2048
	ds_read_b128 v[148:151], v148 offset:3072
	ds_read_b128 v[152:155], v164
	ds_read_b128 v[156:159], v164 offset:1024
	ds_read_b128 v[160:163], v164 offset:2048
	ds_read_b128 v[164:167], v164 offset:3072
	ds_read_b128 v[168:171], v135 offset:32768
	ds_read_b128 v[188:191], v135 offset:33792
	ds_read_b128 v[204:207], v135 offset:34816
	ds_read_b128 v[208:211], v135 offset:35840
	ds_read_b128 v[212:215], v135 offset:36864
	ds_read_b128 v[216:219], v135 offset:37888
	ds_read_b128 v[220:223], v135 offset:38912
	ds_read_b128 v[224:227], v135 offset:39936
	s_waitcnt vmcnt(8)
	s_waitcnt lgkmcnt(0)
	s_barrier
	s_setprio 1
	s_waitcnt lgkmcnt(0)
	v_mfma_f32_16x16x32_bf16 v[124:127], v[136:139], v[168:171], v[124:127]
	v_mfma_f32_16x16x32_bf16 v[120:123], v[144:147], v[168:171], v[120:123]
	v_mfma_f32_16x16x32_bf16 v[112:115], v[136:139], v[204:207], v[112:115]
	v_mfma_f32_16x16x32_bf16 v[104:107], v[144:147], v[204:207], v[104:107]
	v_mfma_f32_16x16x32_bf16 v[96:99], v[136:139], v[212:215], v[96:99]
	v_mfma_f32_16x16x32_bf16 v[88:91], v[144:147], v[212:215], v[88:91]
	v_mfma_f32_16x16x32_bf16 v[80:83], v[136:139], v[220:223], v[80:83]
	v_mfma_f32_16x16x32_bf16 v[72:75], v[144:147], v[220:223], v[72:75]
	v_mfma_f32_16x16x32_bf16 v[124:127], v[140:143], v[188:191], v[124:127]
	v_mfma_f32_16x16x32_bf16 v[120:123], v[148:151], v[188:191], v[120:123]
	v_mfma_f32_16x16x32_bf16 v[112:115], v[140:143], v[208:211], v[112:115]
	v_mfma_f32_16x16x32_bf16 v[104:107], v[148:151], v[208:211], v[104:107]
	v_mfma_f32_16x16x32_bf16 v[96:99], v[140:143], v[216:219], v[96:99]
	v_mfma_f32_16x16x32_bf16 v[88:91], v[148:151], v[216:219], v[88:91]
	v_mfma_f32_16x16x32_bf16 v[80:83], v[140:143], v[224:227], v[80:83]
	v_mfma_f32_16x16x32_bf16 v[72:75], v[148:151], v[224:227], v[72:75]
	s_setprio 0
	s_setprio 1
	v_mfma_f32_16x16x32_bf16 v[116:119], v[152:155], v[168:171], v[116:119]
	v_mfma_f32_16x16x32_bf16 v[108:111], v[160:163], v[168:171], v[108:111]
	v_mfma_f32_16x16x32_bf16 v[100:103], v[152:155], v[204:207], v[100:103]
	v_mfma_f32_16x16x32_bf16 v[92:95], v[160:163], v[204:207], v[92:95]
	v_mfma_f32_16x16x32_bf16 v[84:87], v[152:155], v[212:215], v[84:87]
	v_mfma_f32_16x16x32_bf16 v[76:79], v[160:163], v[212:215], v[76:79]
	v_mfma_f32_16x16x32_bf16 v[68:71], v[152:155], v[220:223], v[68:71]
	v_mfma_f32_16x16x32_bf16 v[64:67], v[160:163], v[220:223], v[64:67]
	v_mfma_f32_16x16x32_bf16 v[116:119], v[156:159], v[188:191], v[116:119]
	v_mfma_f32_16x16x32_bf16 v[108:111], v[164:167], v[188:191], v[108:111]
	v_mfma_f32_16x16x32_bf16 v[100:103], v[156:159], v[208:211], v[100:103]
	v_mfma_f32_16x16x32_bf16 v[92:95], v[164:167], v[208:211], v[92:95]
	v_mfma_f32_16x16x32_bf16 v[84:87], v[156:159], v[216:219], v[84:87]
	v_mfma_f32_16x16x32_bf16 v[76:79], v[164:167], v[216:219], v[76:79]
	v_mfma_f32_16x16x32_bf16 v[68:71], v[156:159], v[224:227], v[68:71]
	v_mfma_f32_16x16x32_bf16 v[64:67], v[164:167], v[224:227], v[64:67]
	s_setprio 0
	s_barrier
	s_add_i32 s26, s62, s31
	v_lshl_add_u64 v[174:175], v[174:175], 0, s[94:95]
	s_mov_b32 m0, s26
	global_load_lds_dwordx4 v[174:175], off
	s_add_i32 m0, s26, 0x2000
	s_add_u32 s24, s24, 0x40080
	v_lshl_add_u64 v[174:175], v[176:177], 0, s[94:95]
	s_addc_u32 s25, s25, 0
	s_add_i32 s26, s63, s31
	global_load_lds_dwordx4 v[174:175], off
	v_lshl_add_u64 v[174:175], s[24:25], 0, v[128:129]
	s_mov_b32 m0, s26
	s_nop 0
	global_load_lds_dwordx4 v[174:175], off
	v_lshl_add_u64 v[174:175], s[24:25], 0, v[132:133]
	s_add_i32 m0, s26, 0x2000
	s_nop 0
	global_load_lds_dwordx4 v[174:175], off
	v_lshl_add_u64 v[174:175], v[180:181], 0, s[94:95]
	s_mov_b32 m0, s54
	s_nop 0
	global_load_lds_dwordx4 v[174:175], off
	v_lshl_add_u64 v[174:175], v[182:183], 0, s[94:95]
	s_mov_b32 m0, s55
	s_nop 0
	global_load_lds_dwordx4 v[174:175], off
	ds_read_b128 v[168:171], v135 offset:49152
	ds_read_b128 v[188:191], v135 offset:50176
	ds_read_b128 v[204:207], v135 offset:51200
	ds_read_b128 v[208:211], v135 offset:52224
	ds_read_b128 v[212:215], v135 offset:53248
	ds_read_b128 v[216:219], v135 offset:54272
	ds_read_b128 v[220:223], v135 offset:55296
	ds_read_b128 v[224:227], v135 offset:56320
	s_waitcnt vmcnt(8)
	s_waitcnt lgkmcnt(0)
	s_barrier
	s_setprio 1
	s_waitcnt lgkmcnt(0)
	v_mfma_f32_16x16x32_bf16 v[60:63], v[136:139], v[168:171], v[60:63]
	v_mfma_f32_16x16x32_bf16 v[56:59], v[144:147], v[168:171], v[56:59]
	v_mfma_f32_16x16x32_bf16 v[48:51], v[136:139], v[204:207], v[48:51]
	v_mfma_f32_16x16x32_bf16 v[40:43], v[144:147], v[204:207], v[40:43]
	v_mfma_f32_16x16x32_bf16 v[32:35], v[136:139], v[212:215], v[32:35]
	v_mfma_f32_16x16x32_bf16 v[24:27], v[144:147], v[212:215], v[24:27]
	v_mfma_f32_16x16x32_bf16 v[16:19], v[136:139], v[220:223], v[16:19]
	v_mfma_f32_16x16x32_bf16 v[8:11], v[144:147], v[220:223], v[8:11]
	v_mfma_f32_16x16x32_bf16 v[60:63], v[140:143], v[188:191], v[60:63]
	v_mfma_f32_16x16x32_bf16 v[56:59], v[148:151], v[188:191], v[56:59]
	v_mfma_f32_16x16x32_bf16 v[48:51], v[140:143], v[208:211], v[48:51]
	v_mfma_f32_16x16x32_bf16 v[40:43], v[148:151], v[208:211], v[40:43]
	v_mfma_f32_16x16x32_bf16 v[32:35], v[140:143], v[216:219], v[32:35]
	v_mfma_f32_16x16x32_bf16 v[24:27], v[148:151], v[216:219], v[24:27]
	v_mfma_f32_16x16x32_bf16 v[16:19], v[140:143], v[224:227], v[16:19]
	v_mfma_f32_16x16x32_bf16 v[8:11], v[148:151], v[224:227], v[8:11]
	s_setprio 0
	s_setprio 1
	v_mfma_f32_16x16x32_bf16 v[52:55], v[152:155], v[168:171], v[52:55]
	v_mfma_f32_16x16x32_bf16 v[44:47], v[160:163], v[168:171], v[44:47]
	v_mfma_f32_16x16x32_bf16 v[36:39], v[152:155], v[204:207], v[36:39]
	v_mfma_f32_16x16x32_bf16 v[28:31], v[160:163], v[204:207], v[28:31]
	v_mfma_f32_16x16x32_bf16 v[20:23], v[152:155], v[212:215], v[20:23]
	v_mfma_f32_16x16x32_bf16 v[12:15], v[160:163], v[212:215], v[12:15]
	v_mfma_f32_16x16x32_bf16 v[4:7], v[152:155], v[220:223], v[4:7]
	v_mfma_f32_16x16x32_bf16 v[0:3], v[160:163], v[220:223], v[0:3]
	v_mfma_f32_16x16x32_bf16 v[52:55], v[156:159], v[188:191], v[52:55]
	v_mfma_f32_16x16x32_bf16 v[44:47], v[164:167], v[188:191], v[44:47]
	v_mfma_f32_16x16x32_bf16 v[36:39], v[156:159], v[208:211], v[36:39]
	v_mfma_f32_16x16x32_bf16 v[28:31], v[164:167], v[208:211], v[28:31]
	v_mfma_f32_16x16x32_bf16 v[20:23], v[156:159], v[216:219], v[20:23]
	v_mfma_f32_16x16x32_bf16 v[12:15], v[164:167], v[216:219], v[12:15]
	v_mfma_f32_16x16x32_bf16 v[4:7], v[156:159], v[224:227], v[4:7]
	v_mfma_f32_16x16x32_bf16 v[0:3], v[164:167], v[224:227], v[0:3]
	s_setprio 0
	s_barrier
	s_add_i32 s61, s61, 2
	s_add_u32 s22, s22, 0x100
	s_addc_u32 s23, s23, 0
	s_add_u32 s15, s15, 0x100
	s_addc_u32 s17, s17, 0
	s_cmp_gt_u32 s61, 13
	s_cbranch_scc0 .LBB0_747
	s_and_b64 vcc, exec, s[12:13]
	s_cbranch_vccz .LBB0_750
	s_barrier

.LBB0_877:
	s_add_i32 s67, s22, 2
	s_add_u32 s23, s6, 0xfffc0080
	s_addc_u32 s24, s7, -1
	s_add_i32 s68, 0, 0x10000
	s_cmp_eq_u32 s19, s22
	s_cselect_b32 s25, s9, s24
	s_cselect_b32 s24, s8, s23
	s_cselect_b32 s23, s21, s27
	s_cselect_b32 s22, s20, s26
	s_add_i32 s70, 0, 0x14000
	v_lshl_add_u64 v[174:175], s[6:7], 0, v[172:173]
	s_add_i32 m0, s37, 0xc000
	global_load_lds_dwordx4 v[174:175], off
	v_lshl_add_u64 v[174:175], s[6:7], 0, v[130:131]
	s_add_i32 m0, s37, 0xe000
	s_nop 0
	global_load_lds_dwordx4 v[174:175], off
	v_add_u32_e32 v148, s68, v134
	v_add_u32_e32 v164, s70, v134
	ds_read_b128 v[136:139], v148
	ds_read_b128 v[140:143], v148 offset:1024
	ds_read_b128 v[144:147], v148 offset:2048
	ds_read_b128 v[148:151], v148 offset:3072
	ds_read_b128 v[152:155], v164
	ds_read_b128 v[156:159], v164 offset:1024
	ds_read_b128 v[160:163], v164 offset:2048
	ds_read_b128 v[164:167], v164 offset:3072
	ds_read_b128 v[168:171], v135
	ds_read_b128 v[188:191], v135 offset:1024
	ds_read_b128 v[204:207], v135 offset:2048
	ds_read_b128 v[208:211], v135 offset:3072
	ds_read_b128 v[212:215], v135 offset:4096
	ds_read_b128 v[216:219], v135 offset:5120
	ds_read_b128 v[220:223], v135 offset:6144
	ds_read_b128 v[224:227], v135 offset:7168
	s_waitcnt vmcnt(8)
	s_waitcnt lgkmcnt(0)
	s_barrier
	s_setprio 1
	s_waitcnt lgkmcnt(0)
	v_mfma_f32_16x16x32_bf16 v[124:127], v[136:139], v[168:171], v[124:127]
	v_mfma_f32_16x16x32_bf16 v[120:123], v[144:147], v[168:171], v[120:123]
	v_mfma_f32_16x16x32_bf16 v[116:119], v[136:139], v[204:207], v[116:119]
	v_mfma_f32_16x16x32_bf16 v[108:111], v[144:147], v[204:207], v[108:111]
	v_mfma_f32_16x16x32_bf16 v[100:103], v[136:139], v[212:215], v[100:103]
	v_mfma_f32_16x16x32_bf16 v[92:95], v[144:147], v[212:215], v[92:95]
	v_mfma_f32_16x16x32_bf16 v[84:87], v[136:139], v[220:223], v[84:87]
	v_mfma_f32_16x16x32_bf16 v[76:79], v[144:147], v[220:223], v[76:79]
	v_mfma_f32_16x16x32_bf16 v[124:127], v[140:143], v[188:191], v[124:127]
	v_mfma_f32_16x16x32_bf16 v[120:123], v[148:151], v[188:191], v[120:123]
	v_mfma_f32_16x16x32_bf16 v[116:119], v[140:143], v[208:211], v[116:119]
	v_mfma_f32_16x16x32_bf16 v[108:111], v[148:151], v[208:211], v[108:111]
	v_mfma_f32_16x16x32_bf16 v[100:103], v[140:143], v[216:219], v[100:103]
	v_mfma_f32_16x16x32_bf16 v[92:95], v[148:151], v[216:219], v[92:95]
	v_mfma_f32_16x16x32_bf16 v[84:87], v[140:143], v[224:227], v[84:87]
	v_mfma_f32_16x16x32_bf16 v[76:79], v[148:151], v[224:227], v[76:79]
	s_setprio 0
	s_setprio 1
	v_mfma_f32_16x16x32_bf16 v[112:115], v[152:155], v[168:171], v[112:115]
	v_mfma_f32_16x16x32_bf16 v[104:107], v[160:163], v[168:171], v[104:107]
	v_mfma_f32_16x16x32_bf16 v[96:99], v[152:155], v[204:207], v[96:99]
	v_mfma_f32_16x16x32_bf16 v[88:91], v[160:163], v[204:207], v[88:91]
	v_mfma_f32_16x16x32_bf16 v[80:83], v[152:155], v[212:215], v[80:83]
	v_mfma_f32_16x16x32_bf16 v[72:75], v[160:163], v[212:215], v[72:75]
	v_mfma_f32_16x16x32_bf16 v[68:71], v[152:155], v[220:223], v[68:71]
	v_mfma_f32_16x16x32_bf16 v[64:67], v[160:163], v[220:223], v[64:67]
	v_mfma_f32_16x16x32_bf16 v[112:115], v[156:159], v[188:191], v[112:115]
	v_mfma_f32_16x16x32_bf16 v[104:107], v[164:167], v[188:191], v[104:107]
	v_mfma_f32_16x16x32_bf16 v[96:99], v[156:159], v[208:211], v[96:99]
	v_mfma_f32_16x16x32_bf16 v[88:91], v[164:167], v[208:211], v[88:91]
	v_mfma_f32_16x16x32_bf16 v[80:83], v[156:159], v[216:219], v[80:83]
	v_mfma_f32_16x16x32_bf16 v[72:75], v[164:167], v[216:219], v[72:75]
	v_mfma_f32_16x16x32_bf16 v[68:71], v[156:159], v[224:227], v[68:71]
	v_mfma_f32_16x16x32_bf16 v[64:67], v[164:167], v[224:227], v[64:67]
	s_setprio 0
	s_barrier
	s_add_i32 s68, s68, s36
	v_lshl_add_u64 v[174:175], s[22:23], 0, v[128:129]
	s_mov_b32 m0, s68
	global_load_lds_dwordx4 v[174:175], off
	s_add_i32 m0, s68, 0x2000
	s_add_u32 s68, s22, 0x40000
	v_lshl_add_u64 v[176:177], s[22:23], 0, v[132:133]
	s_addc_u32 s69, s23, 0
	s_add_i32 s70, s70, s36
	global_load_lds_dwordx4 v[176:177], off
	v_lshl_add_u64 v[180:181], s[68:69], 0, v[128:129]
	s_mov_b32 m0, s70
	v_lshl_add_u64 v[182:183], s[24:25], 0, v[130:131]
	global_load_lds_dwordx4 v[180:181], off
	v_lshl_add_u64 v[180:181], s[68:69], 0, v[132:133]
	s_add_i32 m0, s70, 0x2000
	s_nop 0
	global_load_lds_dwordx4 v[180:181], off
	v_lshl_add_u64 v[180:181], s[24:25], 0, v[172:173]
	s_mov_b32 m0, s37
	s_nop 0
	global_load_lds_dwordx4 v[180:181], off
	s_mov_b32 m0, s38
	s_nop 0
	global_load_lds_dwordx4 v[182:183], off
	ds_read_b128 v[168:171], v135 offset:16384
	ds_read_b128 v[188:191], v135 offset:17408
	ds_read_b128 v[204:207], v135 offset:18432
	ds_read_b128 v[208:211], v135 offset:19456
	ds_read_b128 v[212:215], v135 offset:20480
	ds_read_b128 v[216:219], v135 offset:21504
	ds_read_b128 v[220:223], v135 offset:22528
	ds_read_b128 v[224:227], v135 offset:23552
	s_waitcnt vmcnt(8)
	s_waitcnt lgkmcnt(0)
	s_barrier
	s_setprio 1
	s_waitcnt lgkmcnt(0)
	v_mfma_f32_16x16x32_bf16 v[60:63], v[136:139], v[168:171], v[60:63]
	v_mfma_f32_16x16x32_bf16 v[56:59], v[144:147], v[168:171], v[56:59]
	v_mfma_f32_16x16x32_bf16 v[52:55], v[136:139], v[204:207], v[52:55]
	v_mfma_f32_16x16x32_bf16 v[44:47], v[144:147], v[204:207], v[44:47]
	v_mfma_f32_16x16x32_bf16 v[36:39], v[136:139], v[212:215], v[36:39]
	v_mfma_f32_16x16x32_bf16 v[28:31], v[144:147], v[212:215], v[28:31]
	v_mfma_f32_16x16x32_bf16 v[20:23], v[136:139], v[220:223], v[20:23]
	v_mfma_f32_16x16x32_bf16 v[12:15], v[144:147], v[220:223], v[12:15]
	v_mfma_f32_16x16x32_bf16 v[60:63], v[140:143], v[188:191], v[60:63]
	v_mfma_f32_16x16x32_bf16 v[56:59], v[148:151], v[188:191], v[56:59]
	v_mfma_f32_16x16x32_bf16 v[52:55], v[140:143], v[208:211], v[52:55]
	v_mfma_f32_16x16x32_bf16 v[44:47], v[148:151], v[208:211], v[44:47]
	v_mfma_f32_16x16x32_bf16 v[36:39], v[140:143], v[216:219], v[36:39]
	v_mfma_f32_16x16x32_bf16 v[28:31], v[148:151], v[216:219], v[28:31]
	v_mfma_f32_16x16x32_bf16 v[20:23], v[140:143], v[224:227], v[20:23]
	v_mfma_f32_16x16x32_bf16 v[12:15], v[148:151], v[224:227], v[12:15]
	s_setprio 0
	s_setprio 1
	v_mfma_f32_16x16x32_bf16 v[48:51], v[152:155], v[168:171], v[48:51]
	v_mfma_f32_16x16x32_bf16 v[40:43], v[160:163], v[168:171], v[40:43]
	v_mfma_f32_16x16x32_bf16 v[32:35], v[152:155], v[204:207], v[32:35]
	v_mfma_f32_16x16x32_bf16 v[24:27], v[160:163], v[204:207], v[24:27]
	v_mfma_f32_16x16x32_bf16 v[16:19], v[152:155], v[212:215], v[16:19]
	v_mfma_f32_16x16x32_bf16 v[8:11], v[160:163], v[212:215], v[8:11]
	v_mfma_f32_16x16x32_bf16 v[4:7], v[152:155], v[220:223], v[4:7]
	v_mfma_f32_16x16x32_bf16 v[0:3], v[160:163], v[220:223], v[0:3]
	v_mfma_f32_16x16x32_bf16 v[48:51], v[156:159], v[188:191], v[48:51]
	v_mfma_f32_16x16x32_bf16 v[40:43], v[164:167], v[188:191], v[40:43]
	v_mfma_f32_16x16x32_bf16 v[32:35], v[156:159], v[208:211], v[32:35]
	v_mfma_f32_16x16x32_bf16 v[24:27], v[164:167], v[208:211], v[24:27]
	v_mfma_f32_16x16x32_bf16 v[16:19], v[156:159], v[216:219], v[16:19]
	v_mfma_f32_16x16x32_bf16 v[8:11], v[164:167], v[216:219], v[8:11]
	v_mfma_f32_16x16x32_bf16 v[4:7], v[156:159], v[224:227], v[4:7]
	v_mfma_f32_16x16x32_bf16 v[0:3], v[164:167], v[224:227], v[0:3]
	s_setprio 0
	s_barrier
	s_add_i32 s68, 0, 0x18000
	s_add_i32 s69, 0, 0x1c000
	s_add_u32 s24, s24, 0x40000
	s_addc_u32 s25, s25, 0
	s_mov_b32 m0, s39
	v_lshl_add_u64 v[228:229], s[24:25], 0, v[172:173]
	global_load_lds_dwordx4 v[228:229], off
	v_lshl_add_u64 v[228:229], s[24:25], 0, v[130:131]
	s_mov_b32 m0, s44
	s_nop 0
	global_load_lds_dwordx4 v[228:229], off
	v_add_u32_e32 v148, s68, v134
	v_add_u32_e32 v164, s69, v134
	ds_read_b128 v[136:139], v148
	ds_read_b128 v[140:143], v148 offset:1024
	ds_read_b128 v[144:147], v148 offset:2048
	ds_read_b128 v[148:151], v148 offset:3072
	ds_read_b128 v[152:155], v164
	ds_read_b128 v[156:159], v164 offset:1024
	ds_read_b128 v[160:163], v164 offset:2048
	ds_read_b128 v[164:167], v164 offset:3072
	ds_read_b128 v[168:171], v135 offset:32768
	ds_read_b128 v[188:191], v135 offset:33792
	ds_read_b128 v[204:207], v135 offset:34816
	ds_read_b128 v[208:211], v135 offset:35840
	ds_read_b128 v[212:215], v135 offset:36864
	ds_read_b128 v[216:219], v135 offset:37888
	ds_read_b128 v[220:223], v135 offset:38912
	ds_read_b128 v[224:227], v135 offset:39936
	s_waitcnt vmcnt(8)
	s_waitcnt lgkmcnt(0)
	s_barrier
	s_setprio 1
	s_waitcnt lgkmcnt(0)
	v_mfma_f32_16x16x32_bf16 v[124:127], v[136:139], v[168:171], v[124:127]
	v_mfma_f32_16x16x32_bf16 v[120:123], v[144:147], v[168:171], v[120:123]
	v_mfma_f32_16x16x32_bf16 v[116:119], v[136:139], v[204:207], v[116:119]
	v_mfma_f32_16x16x32_bf16 v[108:111], v[144:147], v[204:207], v[108:111]
	v_mfma_f32_16x16x32_bf16 v[100:103], v[136:139], v[212:215], v[100:103]
	v_mfma_f32_16x16x32_bf16 v[92:95], v[144:147], v[212:215], v[92:95]
	v_mfma_f32_16x16x32_bf16 v[84:87], v[136:139], v[220:223], v[84:87]
	v_mfma_f32_16x16x32_bf16 v[76:79], v[144:147], v[220:223], v[76:79]
	v_mfma_f32_16x16x32_bf16 v[124:127], v[140:143], v[188:191], v[124:127]
	v_mfma_f32_16x16x32_bf16 v[120:123], v[148:151], v[188:191], v[120:123]
	v_mfma_f32_16x16x32_bf16 v[116:119], v[140:143], v[208:211], v[116:119]
	v_mfma_f32_16x16x32_bf16 v[108:111], v[148:151], v[208:211], v[108:111]
	v_mfma_f32_16x16x32_bf16 v[100:103], v[140:143], v[216:219], v[100:103]
	v_mfma_f32_16x16x32_bf16 v[92:95], v[148:151], v[216:219], v[92:95]
	v_mfma_f32_16x16x32_bf16 v[84:87], v[140:143], v[224:227], v[84:87]
	v_mfma_f32_16x16x32_bf16 v[76:79], v[148:151], v[224:227], v[76:79]
	s_setprio 0
	s_setprio 1
	v_mfma_f32_16x16x32_bf16 v[112:115], v[152:155], v[168:171], v[112:115]
	v_mfma_f32_16x16x32_bf16 v[104:107], v[160:163], v[168:171], v[104:107]
	v_mfma_f32_16x16x32_bf16 v[96:99], v[152:155], v[204:207], v[96:99]
	v_mfma_f32_16x16x32_bf16 v[88:91], v[160:163], v[204:207], v[88:91]
	v_mfma_f32_16x16x32_bf16 v[80:83], v[152:155], v[212:215], v[80:83]
	v_mfma_f32_16x16x32_bf16 v[72:75], v[160:163], v[212:215], v[72:75]
	v_mfma_f32_16x16x32_bf16 v[68:71], v[152:155], v[220:223], v[68:71]
	v_mfma_f32_16x16x32_bf16 v[64:67], v[160:163], v[220:223], v[64:67]
	v_mfma_f32_16x16x32_bf16 v[112:115], v[156:159], v[188:191], v[112:115]
	v_mfma_f32_16x16x32_bf16 v[104:107], v[164:167], v[188:191], v[104:107]
	v_mfma_f32_16x16x32_bf16 v[96:99], v[156:159], v[208:211], v[96:99]
	v_mfma_f32_16x16x32_bf16 v[88:91], v[164:167], v[208:211], v[88:91]
	v_mfma_f32_16x16x32_bf16 v[80:83], v[156:159], v[216:219], v[80:83]
	v_mfma_f32_16x16x32_bf16 v[72:75], v[164:167], v[216:219], v[72:75]
	v_mfma_f32_16x16x32_bf16 v[68:71], v[156:159], v[224:227], v[68:71]
	v_mfma_f32_16x16x32_bf16 v[64:67], v[164:167], v[224:227], v[64:67]
	s_setprio 0
	s_barrier
	s_add_i32 s24, s68, s36
	v_lshl_add_u64 v[174:175], v[174:175], 0, s[94:95]
	s_mov_b32 m0, s24
	global_load_lds_dwordx4 v[174:175], off
	s_add_i32 m0, s24, 0x2000
	s_add_u32 s22, s22, 0x40080
	v_lshl_add_u64 v[174:175], v[176:177], 0, s[94:95]
	s_addc_u32 s23, s23, 0
	s_add_i32 s24, s69, s36
	global_load_lds_dwordx4 v[174:175], off
	v_lshl_add_u64 v[174:175], s[22:23], 0, v[128:129]
	s_mov_b32 m0, s24
	s_nop 0
	global_load_lds_dwordx4 v[174:175], off
	v_lshl_add_u64 v[174:175], s[22:23], 0, v[132:133]
	s_add_i32 m0, s24, 0x2000
	s_nop 0
	global_load_lds_dwordx4 v[174:175], off
	v_lshl_add_u64 v[174:175], v[180:181], 0, s[94:95]
	s_mov_b32 m0, s57
	s_nop 0
	global_load_lds_dwordx4 v[174:175], off
	v_lshl_add_u64 v[174:175], v[182:183], 0, s[94:95]
	s_mov_b32 m0, s60
	s_nop 0
	global_load_lds_dwordx4 v[174:175], off
	ds_read_b128 v[168:171], v135 offset:49152
	ds_read_b128 v[188:191], v135 offset:50176
	ds_read_b128 v[204:207], v135 offset:51200
	ds_read_b128 v[208:211], v135 offset:52224
	ds_read_b128 v[212:215], v135 offset:53248
	ds_read_b128 v[216:219], v135 offset:54272
	ds_read_b128 v[220:223], v135 offset:55296
	ds_read_b128 v[224:227], v135 offset:56320
	s_waitcnt vmcnt(8)
	s_waitcnt lgkmcnt(0)
	s_barrier
	s_setprio 1
	s_waitcnt lgkmcnt(0)
	v_mfma_f32_16x16x32_bf16 v[60:63], v[136:139], v[168:171], v[60:63]
	v_mfma_f32_16x16x32_bf16 v[56:59], v[144:147], v[168:171], v[56:59]
	v_mfma_f32_16x16x32_bf16 v[52:55], v[136:139], v[204:207], v[52:55]
	v_mfma_f32_16x16x32_bf16 v[44:47], v[144:147], v[204:207], v[44:47]
	v_mfma_f32_16x16x32_bf16 v[36:39], v[136:139], v[212:215], v[36:39]
	v_mfma_f32_16x16x32_bf16 v[28:31], v[144:147], v[212:215], v[28:31]
	v_mfma_f32_16x16x32_bf16 v[20:23], v[136:139], v[220:223], v[20:23]
	v_mfma_f32_16x16x32_bf16 v[12:15], v[144:147], v[220:223], v[12:15]
	v_mfma_f32_16x16x32_bf16 v[60:63], v[140:143], v[188:191], v[60:63]
	v_mfma_f32_16x16x32_bf16 v[56:59], v[148:151], v[188:191], v[56:59]
	v_mfma_f32_16x16x32_bf16 v[52:55], v[140:143], v[208:211], v[52:55]
	v_mfma_f32_16x16x32_bf16 v[44:47], v[148:151], v[208:211], v[44:47]
	v_mfma_f32_16x16x32_bf16 v[36:39], v[140:143], v[216:219], v[36:39]
	v_mfma_f32_16x16x32_bf16 v[28:31], v[148:151], v[216:219], v[28:31]
	v_mfma_f32_16x16x32_bf16 v[20:23], v[140:143], v[224:227], v[20:23]
	v_mfma_f32_16x16x32_bf16 v[12:15], v[148:151], v[224:227], v[12:15]
	s_setprio 0
	s_setprio 1
	v_mfma_f32_16x16x32_bf16 v[48:51], v[152:155], v[168:171], v[48:51]
	v_mfma_f32_16x16x32_bf16 v[40:43], v[160:163], v[168:171], v[40:43]
	v_mfma_f32_16x16x32_bf16 v[32:35], v[152:155], v[204:207], v[32:35]
	v_mfma_f32_16x16x32_bf16 v[24:27], v[160:163], v[204:207], v[24:27]
	v_mfma_f32_16x16x32_bf16 v[16:19], v[152:155], v[212:215], v[16:19]
	v_mfma_f32_16x16x32_bf16 v[8:11], v[160:163], v[212:215], v[8:11]
	v_mfma_f32_16x16x32_bf16 v[4:7], v[152:155], v[220:223], v[4:7]
	v_mfma_f32_16x16x32_bf16 v[0:3], v[160:163], v[220:223], v[0:3]
	v_mfma_f32_16x16x32_bf16 v[48:51], v[156:159], v[188:191], v[48:51]
	v_mfma_f32_16x16x32_bf16 v[40:43], v[164:167], v[188:191], v[40:43]
	v_mfma_f32_16x16x32_bf16 v[32:35], v[156:159], v[208:211], v[32:35]
	v_mfma_f32_16x16x32_bf16 v[24:27], v[164:167], v[208:211], v[24:27]
	v_mfma_f32_16x16x32_bf16 v[16:19], v[156:159], v[216:219], v[16:19]
	v_mfma_f32_16x16x32_bf16 v[8:11], v[164:167], v[216:219], v[8:11]
	v_mfma_f32_16x16x32_bf16 v[4:7], v[156:159], v[224:227], v[4:7]
	v_mfma_f32_16x16x32_bf16 v[0:3], v[164:167], v[224:227], v[0:3]
	s_setprio 0
	s_barrier
	s_add_u32 s6, s6, 0x100
	s_addc_u32 s7, s7, 0
	s_add_u32 s26, s26, 0x100
	s_addc_u32 s27, s27, 0
	s_cmp_ge_i32 s67, s64
	s_mov_b32 s22, s67
	s_cbranch_scc0 .LBB0_877
	s_and_b64 vcc, exec, s[14:15]
	s_cbranch_vccz .LBB0_880
	s_barrier

.LBB0_990:
	s_add_u32 s8, s6, 0xfffe0080
	s_addc_u32 s9, s7, -1
	s_add_i32 s70, 0, 0x10000
	s_cmp_eq_u32 s69, 12
	s_cselect_b32 s11, s27, s9
	s_cselect_b32 s10, s26, s8
	s_cselect_b32 s9, s29, s31
	s_cselect_b32 s8, s28, s25
	s_add_i32 s72, 0, 0x14000
	v_lshl_add_u64 v[174:175], s[6:7], 0, v[172:173]
	s_add_i32 m0, s44, 0xc000
	global_load_lds_dwordx4 v[174:175], off
	v_lshl_add_u64 v[174:175], s[6:7], 0, v[132:133]
	s_add_i32 m0, s44, 0xe000
	s_nop 0
	global_load_lds_dwordx4 v[174:175], off
	v_add_u32_e32 v148, s70, v134
	v_add_u32_e32 v164, s72, v134
	ds_read_b128 v[136:139], v148
	ds_read_b128 v[140:143], v148 offset:1024
	ds_read_b128 v[144:147], v148 offset:2048
	ds_read_b128 v[148:151], v148 offset:3072
	ds_read_b128 v[152:155], v164
	ds_read_b128 v[156:159], v164 offset:1024
	ds_read_b128 v[160:163], v164 offset:2048
	ds_read_b128 v[164:167], v164 offset:3072
	ds_read_b128 v[168:171], v135
	ds_read_b128 v[188:191], v135 offset:1024
	ds_read_b128 v[204:207], v135 offset:2048
	ds_read_b128 v[208:211], v135 offset:3072
	ds_read_b128 v[212:215], v135 offset:4096
	ds_read_b128 v[216:219], v135 offset:5120
	ds_read_b128 v[220:223], v135 offset:6144
	ds_read_b128 v[224:227], v135 offset:7168
	s_waitcnt vmcnt(8)
	s_waitcnt lgkmcnt(0)
	s_barrier
	s_setprio 1
	s_waitcnt lgkmcnt(0)
	v_mfma_f32_16x16x32_bf16 v[124:127], v[136:139], v[168:171], v[124:127]
	v_mfma_f32_16x16x32_bf16 v[120:123], v[144:147], v[168:171], v[120:123]
	v_mfma_f32_16x16x32_bf16 v[108:111], v[136:139], v[204:207], v[108:111]
	v_mfma_f32_16x16x32_bf16 v[104:107], v[144:147], v[204:207], v[104:107]
	v_mfma_f32_16x16x32_bf16 v[92:95], v[136:139], v[212:215], v[92:95]
	v_mfma_f32_16x16x32_bf16 v[88:91], v[144:147], v[212:215], v[88:91]
	v_mfma_f32_16x16x32_bf16 v[76:79], v[136:139], v[220:223], v[76:79]
	v_mfma_f32_16x16x32_bf16 v[72:75], v[144:147], v[220:223], v[72:75]
	v_mfma_f32_16x16x32_bf16 v[124:127], v[140:143], v[188:191], v[124:127]
	v_mfma_f32_16x16x32_bf16 v[120:123], v[148:151], v[188:191], v[120:123]
	v_mfma_f32_16x16x32_bf16 v[108:111], v[140:143], v[208:211], v[108:111]
	v_mfma_f32_16x16x32_bf16 v[104:107], v[148:151], v[208:211], v[104:107]
	v_mfma_f32_16x16x32_bf16 v[92:95], v[140:143], v[216:219], v[92:95]
	v_mfma_f32_16x16x32_bf16 v[88:91], v[148:151], v[216:219], v[88:91]
	v_mfma_f32_16x16x32_bf16 v[76:79], v[140:143], v[224:227], v[76:79]
	v_mfma_f32_16x16x32_bf16 v[72:75], v[148:151], v[224:227], v[72:75]
	s_setprio 0
	s_setprio 1
	v_mfma_f32_16x16x32_bf16 v[116:119], v[152:155], v[168:171], v[116:119]
	v_mfma_f32_16x16x32_bf16 v[112:115], v[160:163], v[168:171], v[112:115]
	v_mfma_f32_16x16x32_bf16 v[100:103], v[152:155], v[204:207], v[100:103]
	v_mfma_f32_16x16x32_bf16 v[96:99], v[160:163], v[204:207], v[96:99]
	v_mfma_f32_16x16x32_bf16 v[84:87], v[152:155], v[212:215], v[84:87]
	v_mfma_f32_16x16x32_bf16 v[80:83], v[160:163], v[212:215], v[80:83]
	v_mfma_f32_16x16x32_bf16 v[68:71], v[152:155], v[220:223], v[68:71]
	v_mfma_f32_16x16x32_bf16 v[64:67], v[160:163], v[220:223], v[64:67]
	v_mfma_f32_16x16x32_bf16 v[116:119], v[156:159], v[188:191], v[116:119]
	v_mfma_f32_16x16x32_bf16 v[112:115], v[164:167], v[188:191], v[112:115]
	v_mfma_f32_16x16x32_bf16 v[100:103], v[156:159], v[208:211], v[100:103]
	v_mfma_f32_16x16x32_bf16 v[96:99], v[164:167], v[208:211], v[96:99]
	v_mfma_f32_16x16x32_bf16 v[84:87], v[156:159], v[216:219], v[84:87]
	v_mfma_f32_16x16x32_bf16 v[80:83], v[164:167], v[216:219], v[80:83]
	v_mfma_f32_16x16x32_bf16 v[68:71], v[156:159], v[224:227], v[68:71]
	v_mfma_f32_16x16x32_bf16 v[64:67], v[164:167], v[224:227], v[64:67]
	s_setprio 0
	s_barrier
	s_add_i32 s70, s70, s39
	v_lshl_add_u64 v[174:175], s[8:9], 0, v[128:129]
	s_mov_b32 m0, s70
	global_load_lds_dwordx4 v[174:175], off
	s_add_i32 m0, s70, 0x2000
	s_add_u32 s70, s8, 0x40000
	v_lshl_add_u64 v[176:177], s[8:9], 0, v[130:131]
	s_addc_u32 s71, s9, 0
	s_add_i32 s72, s72, s39
	global_load_lds_dwordx4 v[176:177], off
	v_lshl_add_u64 v[180:181], s[70:71], 0, v[128:129]
	s_mov_b32 m0, s72
	v_lshl_add_u64 v[182:183], s[10:11], 0, v[132:133]
	global_load_lds_dwordx4 v[180:181], off
	v_lshl_add_u64 v[180:181], s[70:71], 0, v[130:131]
	s_add_i32 m0, s72, 0x2000
	s_nop 0
	global_load_lds_dwordx4 v[180:181], off
	v_lshl_add_u64 v[180:181], s[10:11], 0, v[172:173]
	s_mov_b32 m0, s44
	s_nop 0
	global_load_lds_dwordx4 v[180:181], off
	s_mov_b32 m0, s45
	s_nop 0
	global_load_lds_dwordx4 v[182:183], off
	ds_read_b128 v[168:171], v135 offset:16384
	ds_read_b128 v[188:191], v135 offset:17408
	ds_read_b128 v[204:207], v135 offset:18432
	ds_read_b128 v[208:211], v135 offset:19456
	ds_read_b128 v[212:215], v135 offset:20480
	ds_read_b128 v[216:219], v135 offset:21504
	ds_read_b128 v[220:223], v135 offset:22528
	ds_read_b128 v[224:227], v135 offset:23552
	s_waitcnt vmcnt(8)
	s_waitcnt lgkmcnt(0)
	s_barrier
	s_setprio 1
	s_waitcnt lgkmcnt(0)
	v_mfma_f32_16x16x32_bf16 v[60:63], v[136:139], v[168:171], v[60:63]
	v_mfma_f32_16x16x32_bf16 v[56:59], v[144:147], v[168:171], v[56:59]
	v_mfma_f32_16x16x32_bf16 v[44:47], v[136:139], v[204:207], v[44:47]
	v_mfma_f32_16x16x32_bf16 v[40:43], v[144:147], v[204:207], v[40:43]
	v_mfma_f32_16x16x32_bf16 v[28:31], v[136:139], v[212:215], v[28:31]
	v_mfma_f32_16x16x32_bf16 v[24:27], v[144:147], v[212:215], v[24:27]
	v_mfma_f32_16x16x32_bf16 v[4:7], v[136:139], v[220:223], v[4:7]
	v_mfma_f32_16x16x32_bf16 v[12:15], v[144:147], v[220:223], v[12:15]
	v_mfma_f32_16x16x32_bf16 v[60:63], v[140:143], v[188:191], v[60:63]
	v_mfma_f32_16x16x32_bf16 v[56:59], v[148:151], v[188:191], v[56:59]
	v_mfma_f32_16x16x32_bf16 v[44:47], v[140:143], v[208:211], v[44:47]
	v_mfma_f32_16x16x32_bf16 v[40:43], v[148:151], v[208:211], v[40:43]
	v_mfma_f32_16x16x32_bf16 v[28:31], v[140:143], v[216:219], v[28:31]
	v_mfma_f32_16x16x32_bf16 v[24:27], v[148:151], v[216:219], v[24:27]
	v_mfma_f32_16x16x32_bf16 v[4:7], v[140:143], v[224:227], v[4:7]
	v_mfma_f32_16x16x32_bf16 v[12:15], v[148:151], v[224:227], v[12:15]
	s_setprio 0
	s_setprio 1
	v_mfma_f32_16x16x32_bf16 v[52:55], v[152:155], v[168:171], v[52:55]
	v_mfma_f32_16x16x32_bf16 v[48:51], v[160:163], v[168:171], v[48:51]
	v_mfma_f32_16x16x32_bf16 v[36:39], v[152:155], v[204:207], v[36:39]
	v_mfma_f32_16x16x32_bf16 v[32:35], v[160:163], v[204:207], v[32:35]
	v_mfma_f32_16x16x32_bf16 v[20:23], v[152:155], v[212:215], v[20:23]
	v_mfma_f32_16x16x32_bf16 v[16:19], v[160:163], v[212:215], v[16:19]
	v_mfma_f32_16x16x32_bf16 v[8:11], v[152:155], v[220:223], v[8:11]
	v_mfma_f32_16x16x32_bf16 v[0:3], v[160:163], v[220:223], v[0:3]
	v_mfma_f32_16x16x32_bf16 v[52:55], v[156:159], v[188:191], v[52:55]
	v_mfma_f32_16x16x32_bf16 v[48:51], v[164:167], v[188:191], v[48:51]
	v_mfma_f32_16x16x32_bf16 v[36:39], v[156:159], v[208:211], v[36:39]
	v_mfma_f32_16x16x32_bf16 v[32:35], v[164:167], v[208:211], v[32:35]
	v_mfma_f32_16x16x32_bf16 v[20:23], v[156:159], v[216:219], v[20:23]
	v_mfma_f32_16x16x32_bf16 v[16:19], v[164:167], v[216:219], v[16:19]
	v_mfma_f32_16x16x32_bf16 v[8:11], v[156:159], v[224:227], v[8:11]
	v_mfma_f32_16x16x32_bf16 v[0:3], v[164:167], v[224:227], v[0:3]
	s_setprio 0
	s_barrier
	s_add_i32 s70, 0, 0x18000
	s_add_i32 s71, 0, 0x1c000
	s_add_u32 s10, s10, 0x20000
	s_addc_u32 s11, s11, 0
	s_mov_b32 m0, s54
	v_lshl_add_u64 v[228:229], s[10:11], 0, v[172:173]
	global_load_lds_dwordx4 v[228:229], off
	v_lshl_add_u64 v[228:229], s[10:11], 0, v[132:133]
	s_mov_b32 m0, s55
	s_nop 0
	global_load_lds_dwordx4 v[228:229], off
	v_add_u32_e32 v148, s70, v134
	v_add_u32_e32 v164, s71, v134
	ds_read_b128 v[136:139], v148
	ds_read_b128 v[140:143], v148 offset:1024
	ds_read_b128 v[144:147], v148 offset:2048
	ds_read_b128 v[148:151], v148 offset:3072
	ds_read_b128 v[152:155], v164
	ds_read_b128 v[156:159], v164 offset:1024
	ds_read_b128 v[160:163], v164 offset:2048
	ds_read_b128 v[164:167], v164 offset:3072
	ds_read_b128 v[168:171], v135 offset:32768
	ds_read_b128 v[188:191], v135 offset:33792
	ds_read_b128 v[204:207], v135 offset:34816
	ds_read_b128 v[208:211], v135 offset:35840
	ds_read_b128 v[212:215], v135 offset:36864
	ds_read_b128 v[216:219], v135 offset:37888
	ds_read_b128 v[220:223], v135 offset:38912
	ds_read_b128 v[224:227], v135 offset:39936
	s_waitcnt vmcnt(8)
	s_waitcnt lgkmcnt(0)
	s_barrier
	s_setprio 1
	s_waitcnt lgkmcnt(0)
	v_mfma_f32_16x16x32_bf16 v[124:127], v[136:139], v[168:171], v[124:127]
	v_mfma_f32_16x16x32_bf16 v[120:123], v[144:147], v[168:171], v[120:123]
	v_mfma_f32_16x16x32_bf16 v[108:111], v[136:139], v[204:207], v[108:111]
	v_mfma_f32_16x16x32_bf16 v[104:107], v[144:147], v[204:207], v[104:107]
	v_mfma_f32_16x16x32_bf16 v[92:95], v[136:139], v[212:215], v[92:95]
	v_mfma_f32_16x16x32_bf16 v[88:91], v[144:147], v[212:215], v[88:91]
	v_mfma_f32_16x16x32_bf16 v[76:79], v[136:139], v[220:223], v[76:79]
	v_mfma_f32_16x16x32_bf16 v[72:75], v[144:147], v[220:223], v[72:75]
	v_mfma_f32_16x16x32_bf16 v[124:127], v[140:143], v[188:191], v[124:127]
	v_mfma_f32_16x16x32_bf16 v[120:123], v[148:151], v[188:191], v[120:123]
	v_mfma_f32_16x16x32_bf16 v[108:111], v[140:143], v[208:211], v[108:111]
	v_mfma_f32_16x16x32_bf16 v[104:107], v[148:151], v[208:211], v[104:107]
	v_mfma_f32_16x16x32_bf16 v[92:95], v[140:143], v[216:219], v[92:95]
	v_mfma_f32_16x16x32_bf16 v[88:91], v[148:151], v[216:219], v[88:91]
	v_mfma_f32_16x16x32_bf16 v[76:79], v[140:143], v[224:227], v[76:79]
	v_mfma_f32_16x16x32_bf16 v[72:75], v[148:151], v[224:227], v[72:75]
	s_setprio 0
	s_setprio 1
	v_mfma_f32_16x16x32_bf16 v[116:119], v[152:155], v[168:171], v[116:119]
	v_mfma_f32_16x16x32_bf16 v[112:115], v[160:163], v[168:171], v[112:115]
	v_mfma_f32_16x16x32_bf16 v[100:103], v[152:155], v[204:207], v[100:103]
	v_mfma_f32_16x16x32_bf16 v[96:99], v[160:163], v[204:207], v[96:99]
	v_mfma_f32_16x16x32_bf16 v[84:87], v[152:155], v[212:215], v[84:87]
	v_mfma_f32_16x16x32_bf16 v[80:83], v[160:163], v[212:215], v[80:83]
	v_mfma_f32_16x16x32_bf16 v[68:71], v[152:155], v[220:223], v[68:71]
	v_mfma_f32_16x16x32_bf16 v[64:67], v[160:163], v[220:223], v[64:67]
	v_mfma_f32_16x16x32_bf16 v[116:119], v[156:159], v[188:191], v[116:119]
	v_mfma_f32_16x16x32_bf16 v[112:115], v[164:167], v[188:191], v[112:115]
	v_mfma_f32_16x16x32_bf16 v[100:103], v[156:159], v[208:211], v[100:103]
	v_mfma_f32_16x16x32_bf16 v[96:99], v[164:167], v[208:211], v[96:99]
	v_mfma_f32_16x16x32_bf16 v[84:87], v[156:159], v[216:219], v[84:87]
	v_mfma_f32_16x16x32_bf16 v[80:83], v[164:167], v[216:219], v[80:83]
	v_mfma_f32_16x16x32_bf16 v[68:71], v[156:159], v[224:227], v[68:71]
	v_mfma_f32_16x16x32_bf16 v[64:67], v[164:167], v[224:227], v[64:67]
	s_setprio 0
	s_barrier
	s_add_i32 s10, s70, s39
	v_lshl_add_u64 v[174:175], v[174:175], 0, s[94:95]
	s_mov_b32 m0, s10
	global_load_lds_dwordx4 v[174:175], off
	s_add_i32 m0, s10, 0x2000
	s_add_u32 s8, s8, 0x40080
	v_lshl_add_u64 v[174:175], v[176:177], 0, s[94:95]
	s_addc_u32 s9, s9, 0
	s_add_i32 s10, s71, s39
	global_load_lds_dwordx4 v[174:175], off
	v_lshl_add_u64 v[174:175], s[8:9], 0, v[128:129]
	s_mov_b32 m0, s10
	s_nop 0
	global_load_lds_dwordx4 v[174:175], off
	v_lshl_add_u64 v[174:175], s[8:9], 0, v[130:131]
	s_add_i32 m0, s10, 0x2000
	s_nop 0
	global_load_lds_dwordx4 v[174:175], off
	v_lshl_add_u64 v[174:175], v[180:181], 0, s[94:95]
	s_mov_b32 m0, s64
	s_nop 0
	global_load_lds_dwordx4 v[174:175], off
	v_lshl_add_u64 v[174:175], v[182:183], 0, s[94:95]
	s_mov_b32 m0, s65
	s_nop 0
	global_load_lds_dwordx4 v[174:175], off
	ds_read_b128 v[168:171], v135 offset:49152
	ds_read_b128 v[188:191], v135 offset:50176
	ds_read_b128 v[204:207], v135 offset:51200
	ds_read_b128 v[208:211], v135 offset:52224
	ds_read_b128 v[212:215], v135 offset:53248
	ds_read_b128 v[216:219], v135 offset:54272
	ds_read_b128 v[220:223], v135 offset:55296
	ds_read_b128 v[224:227], v135 offset:56320
	s_waitcnt vmcnt(8)
	s_waitcnt lgkmcnt(0)
	s_barrier
	s_setprio 1
	s_waitcnt lgkmcnt(0)
	v_mfma_f32_16x16x32_bf16 v[60:63], v[136:139], v[168:171], v[60:63]
	v_mfma_f32_16x16x32_bf16 v[56:59], v[144:147], v[168:171], v[56:59]
	v_mfma_f32_16x16x32_bf16 v[44:47], v[136:139], v[204:207], v[44:47]
	v_mfma_f32_16x16x32_bf16 v[40:43], v[144:147], v[204:207], v[40:43]
	v_mfma_f32_16x16x32_bf16 v[28:31], v[136:139], v[212:215], v[28:31]
	v_mfma_f32_16x16x32_bf16 v[24:27], v[144:147], v[212:215], v[24:27]
	v_mfma_f32_16x16x32_bf16 v[4:7], v[136:139], v[220:223], v[4:7]
	v_mfma_f32_16x16x32_bf16 v[12:15], v[144:147], v[220:223], v[12:15]
	v_mfma_f32_16x16x32_bf16 v[60:63], v[140:143], v[188:191], v[60:63]
	v_mfma_f32_16x16x32_bf16 v[56:59], v[148:151], v[188:191], v[56:59]
	v_mfma_f32_16x16x32_bf16 v[44:47], v[140:143], v[208:211], v[44:47]
	v_mfma_f32_16x16x32_bf16 v[40:43], v[148:151], v[208:211], v[40:43]
	v_mfma_f32_16x16x32_bf16 v[28:31], v[140:143], v[216:219], v[28:31]
	v_mfma_f32_16x16x32_bf16 v[24:27], v[148:151], v[216:219], v[24:27]
	v_mfma_f32_16x16x32_bf16 v[4:7], v[140:143], v[224:227], v[4:7]
	v_mfma_f32_16x16x32_bf16 v[12:15], v[148:151], v[224:227], v[12:15]
	s_setprio 0
	s_setprio 1
	v_mfma_f32_16x16x32_bf16 v[52:55], v[152:155], v[168:171], v[52:55]
	v_mfma_f32_16x16x32_bf16 v[48:51], v[160:163], v[168:171], v[48:51]
	v_mfma_f32_16x16x32_bf16 v[36:39], v[152:155], v[204:207], v[36:39]
	v_mfma_f32_16x16x32_bf16 v[32:35], v[160:163], v[204:207], v[32:35]
	v_mfma_f32_16x16x32_bf16 v[20:23], v[152:155], v[212:215], v[20:23]
	v_mfma_f32_16x16x32_bf16 v[16:19], v[160:163], v[212:215], v[16:19]
	v_mfma_f32_16x16x32_bf16 v[8:11], v[152:155], v[220:223], v[8:11]
	v_mfma_f32_16x16x32_bf16 v[0:3], v[160:163], v[220:223], v[0:3]
	v_mfma_f32_16x16x32_bf16 v[52:55], v[156:159], v[188:191], v[52:55]
	v_mfma_f32_16x16x32_bf16 v[48:51], v[164:167], v[188:191], v[48:51]
	v_mfma_f32_16x16x32_bf16 v[36:39], v[156:159], v[208:211], v[36:39]
	v_mfma_f32_16x16x32_bf16 v[32:35], v[164:167], v[208:211], v[32:35]
	v_mfma_f32_16x16x32_bf16 v[20:23], v[156:159], v[216:219], v[20:23]
	v_mfma_f32_16x16x32_bf16 v[16:19], v[164:167], v[216:219], v[16:19]
	v_mfma_f32_16x16x32_bf16 v[8:11], v[156:159], v[224:227], v[8:11]
	v_mfma_f32_16x16x32_bf16 v[0:3], v[164:167], v[224:227], v[0:3]
	s_setprio 0
	s_barrier
	s_add_i32 s69, s69, 2
	s_add_u32 s6, s6, 0x100
	s_addc_u32 s7, s7, 0
	s_add_u32 s25, s25, 0x100
	s_addc_u32 s31, s31, 0
	s_cmp_gt_u32 s69, 13
	s_cbranch_scc0 .LBB0_990
	s_and_b64 vcc, exec, s[22:23]
	s_cbranch_vccz .LBB0_993
	s_barrier

.LBB0_1057:
	s_add_i32 s69, s20, 2
	s_add_u32 s21, s6, 0xfff50080
	s_addc_u32 s22, s7, -1
	s_add_i32 s70, 0, 0x10000
	s_cmp_eq_u32 s24, s20
	s_cselect_b32 s23, s9, s22
	s_cselect_b32 s22, s8, s21
	s_cselect_b32 s21, s19, s68
	s_cselect_b32 s20, s18, s25
	s_add_i32 s72, 0, 0x14000
	v_lshl_add_u64 v[220:221], s[6:7], 0, v[172:173]
	s_add_i32 m0, s35, 0xc000
	global_load_lds_dwordx4 v[220:221], off
	v_lshl_add_u64 v[220:221], s[6:7], 0, v[130:131]
	s_add_i32 m0, s35, 0xe000
	s_nop 0
	global_load_lds_dwordx4 v[220:221], off
	v_add_u32_e32 v148, s70, v134
	v_add_u32_e32 v164, s72, v134
	ds_read_b128 v[136:139], v148
	ds_read_b128 v[140:143], v148 offset:1024
	ds_read_b128 v[144:147], v148 offset:2048
	ds_read_b128 v[148:151], v148 offset:3072
	ds_read_b128 v[152:155], v164
	ds_read_b128 v[156:159], v164 offset:1024
	ds_read_b128 v[160:163], v164 offset:2048
	ds_read_b128 v[164:167], v164 offset:3072
	ds_read_b128 v[168:171], v135
	ds_read_b128 v[174:177], v135 offset:1024
	ds_read_b128 v[180:183], v135 offset:2048
	ds_read_b128 v[188:191], v135 offset:3072
	ds_read_b128 v[204:207], v135 offset:4096
	ds_read_b128 v[208:211], v135 offset:5120
	ds_read_b128 v[212:215], v135 offset:6144
	ds_read_b128 v[216:219], v135 offset:7168
	s_waitcnt vmcnt(8)
	s_waitcnt lgkmcnt(0)
	s_barrier
	s_setprio 1
	s_waitcnt lgkmcnt(0)
	v_mfma_f32_16x16x32_bf16 v[124:127], v[136:139], v[168:171], v[124:127]
	v_mfma_f32_16x16x32_bf16 v[120:123], v[144:147], v[168:171], v[120:123]
	v_mfma_f32_16x16x32_bf16 v[116:119], v[136:139], v[180:183], v[116:119]
	v_mfma_f32_16x16x32_bf16 v[108:111], v[144:147], v[180:183], v[108:111]
	v_mfma_f32_16x16x32_bf16 v[100:103], v[136:139], v[204:207], v[100:103]
	v_mfma_f32_16x16x32_bf16 v[92:95], v[144:147], v[204:207], v[92:95]
	v_mfma_f32_16x16x32_bf16 v[84:87], v[136:139], v[212:215], v[84:87]
	v_mfma_f32_16x16x32_bf16 v[76:79], v[144:147], v[212:215], v[76:79]
	v_mfma_f32_16x16x32_bf16 v[124:127], v[140:143], v[174:177], v[124:127]
	v_mfma_f32_16x16x32_bf16 v[120:123], v[148:151], v[174:177], v[120:123]
	v_mfma_f32_16x16x32_bf16 v[116:119], v[140:143], v[188:191], v[116:119]
	v_mfma_f32_16x16x32_bf16 v[108:111], v[148:151], v[188:191], v[108:111]
	v_mfma_f32_16x16x32_bf16 v[100:103], v[140:143], v[208:211], v[100:103]
	v_mfma_f32_16x16x32_bf16 v[92:95], v[148:151], v[208:211], v[92:95]
	v_mfma_f32_16x16x32_bf16 v[84:87], v[140:143], v[216:219], v[84:87]
	v_mfma_f32_16x16x32_bf16 v[76:79], v[148:151], v[216:219], v[76:79]
	s_setprio 0
	s_setprio 1
	v_mfma_f32_16x16x32_bf16 v[112:115], v[152:155], v[168:171], v[112:115]
	v_mfma_f32_16x16x32_bf16 v[104:107], v[160:163], v[168:171], v[104:107]
	v_mfma_f32_16x16x32_bf16 v[96:99], v[152:155], v[180:183], v[96:99]
	v_mfma_f32_16x16x32_bf16 v[88:91], v[160:163], v[180:183], v[88:91]
	v_mfma_f32_16x16x32_bf16 v[80:83], v[152:155], v[204:207], v[80:83]
	v_mfma_f32_16x16x32_bf16 v[72:75], v[160:163], v[204:207], v[72:75]
	v_mfma_f32_16x16x32_bf16 v[68:71], v[152:155], v[212:215], v[68:71]
	v_mfma_f32_16x16x32_bf16 v[64:67], v[160:163], v[212:215], v[64:67]
	v_mfma_f32_16x16x32_bf16 v[112:115], v[156:159], v[174:177], v[112:115]
	v_mfma_f32_16x16x32_bf16 v[104:107], v[164:167], v[174:177], v[104:107]
	v_mfma_f32_16x16x32_bf16 v[96:99], v[156:159], v[188:191], v[96:99]
	v_mfma_f32_16x16x32_bf16 v[88:91], v[164:167], v[188:191], v[88:91]
	v_mfma_f32_16x16x32_bf16 v[80:83], v[156:159], v[208:211], v[80:83]
	v_mfma_f32_16x16x32_bf16 v[72:75], v[164:167], v[208:211], v[72:75]
	v_mfma_f32_16x16x32_bf16 v[68:71], v[156:159], v[216:219], v[68:71]
	v_mfma_f32_16x16x32_bf16 v[64:67], v[164:167], v[216:219], v[64:67]
	s_setprio 0
	s_barrier
	s_add_i32 s70, s70, s34
	v_lshl_add_u64 v[220:221], s[20:21], 0, v[128:129]
	s_mov_b32 m0, s70
	global_load_lds_dwordx4 v[220:221], off
	s_add_i32 m0, s70, 0x2000
	s_add_u32 s70, s20, 0xb0000
	v_lshl_add_u64 v[222:223], s[20:21], 0, v[132:133]
	s_addc_u32 s71, s21, 0
	s_add_i32 s72, s72, s34
	global_load_lds_dwordx4 v[222:223], off
	v_lshl_add_u64 v[224:225], s[70:71], 0, v[128:129]
	s_mov_b32 m0, s72
	v_lshl_add_u64 v[226:227], s[22:23], 0, v[130:131]
	global_load_lds_dwordx4 v[224:225], off
	v_lshl_add_u64 v[224:225], s[70:71], 0, v[132:133]
	s_add_i32 m0, s72, 0x2000
	s_nop 0
	global_load_lds_dwordx4 v[224:225], off
	v_lshl_add_u64 v[224:225], s[22:23], 0, v[172:173]
	s_mov_b32 m0, s35
	s_nop 0
	global_load_lds_dwordx4 v[224:225], off
	s_mov_b32 m0, s36
	s_nop 0
	global_load_lds_dwordx4 v[226:227], off
	ds_read_b128 v[168:171], v135 offset:16384
	ds_read_b128 v[174:177], v135 offset:17408
	ds_read_b128 v[180:183], v135 offset:18432
	ds_read_b128 v[188:191], v135 offset:19456
	ds_read_b128 v[204:207], v135 offset:20480
	ds_read_b128 v[208:211], v135 offset:21504
	ds_read_b128 v[212:215], v135 offset:22528
	ds_read_b128 v[216:219], v135 offset:23552
	s_waitcnt vmcnt(8)
	s_waitcnt lgkmcnt(0)
	s_barrier
	s_setprio 1
	s_waitcnt lgkmcnt(0)
	v_mfma_f32_16x16x32_bf16 v[60:63], v[136:139], v[168:171], v[60:63]
	v_mfma_f32_16x16x32_bf16 v[56:59], v[144:147], v[168:171], v[56:59]
	v_mfma_f32_16x16x32_bf16 v[52:55], v[136:139], v[180:183], v[52:55]
	v_mfma_f32_16x16x32_bf16 v[44:47], v[144:147], v[180:183], v[44:47]
	v_mfma_f32_16x16x32_bf16 v[36:39], v[136:139], v[204:207], v[36:39]
	v_mfma_f32_16x16x32_bf16 v[28:31], v[144:147], v[204:207], v[28:31]
	v_mfma_f32_16x16x32_bf16 v[20:23], v[136:139], v[212:215], v[20:23]
	v_mfma_f32_16x16x32_bf16 v[12:15], v[144:147], v[212:215], v[12:15]
	v_mfma_f32_16x16x32_bf16 v[60:63], v[140:143], v[174:177], v[60:63]
	v_mfma_f32_16x16x32_bf16 v[56:59], v[148:151], v[174:177], v[56:59]
	v_mfma_f32_16x16x32_bf16 v[52:55], v[140:143], v[188:191], v[52:55]
	v_mfma_f32_16x16x32_bf16 v[44:47], v[148:151], v[188:191], v[44:47]
	v_mfma_f32_16x16x32_bf16 v[36:39], v[140:143], v[208:211], v[36:39]
	v_mfma_f32_16x16x32_bf16 v[28:31], v[148:151], v[208:211], v[28:31]
	v_mfma_f32_16x16x32_bf16 v[20:23], v[140:143], v[216:219], v[20:23]
	v_mfma_f32_16x16x32_bf16 v[12:15], v[148:151], v[216:219], v[12:15]
	s_setprio 0
	s_setprio 1
	v_mfma_f32_16x16x32_bf16 v[48:51], v[152:155], v[168:171], v[48:51]
	v_mfma_f32_16x16x32_bf16 v[40:43], v[160:163], v[168:171], v[40:43]
	v_mfma_f32_16x16x32_bf16 v[32:35], v[152:155], v[180:183], v[32:35]
	v_mfma_f32_16x16x32_bf16 v[24:27], v[160:163], v[180:183], v[24:27]
	v_mfma_f32_16x16x32_bf16 v[16:19], v[152:155], v[204:207], v[16:19]
	v_mfma_f32_16x16x32_bf16 v[8:11], v[160:163], v[204:207], v[8:11]
	v_mfma_f32_16x16x32_bf16 v[4:7], v[152:155], v[212:215], v[4:7]
	v_mfma_f32_16x16x32_bf16 v[0:3], v[160:163], v[212:215], v[0:3]
	v_mfma_f32_16x16x32_bf16 v[48:51], v[156:159], v[174:177], v[48:51]
	v_mfma_f32_16x16x32_bf16 v[40:43], v[164:167], v[174:177], v[40:43]
	v_mfma_f32_16x16x32_bf16 v[32:35], v[156:159], v[188:191], v[32:35]
	v_mfma_f32_16x16x32_bf16 v[24:27], v[164:167], v[188:191], v[24:27]
	v_mfma_f32_16x16x32_bf16 v[16:19], v[156:159], v[208:211], v[16:19]
	v_mfma_f32_16x16x32_bf16 v[8:11], v[164:167], v[208:211], v[8:11]
	v_mfma_f32_16x16x32_bf16 v[4:7], v[156:159], v[216:219], v[4:7]
	v_mfma_f32_16x16x32_bf16 v[0:3], v[164:167], v[216:219], v[0:3]
	s_setprio 0
	s_barrier
	s_add_i32 s70, 0, 0x18000
	s_add_i32 s71, 0, 0x1c000
	s_add_u32 s22, s22, 0xb0000
	s_addc_u32 s23, s23, 0
	s_mov_b32 m0, s37
	v_lshl_add_u64 v[228:229], s[22:23], 0, v[172:173]
	global_load_lds_dwordx4 v[228:229], off
	v_lshl_add_u64 v[228:229], s[22:23], 0, v[130:131]
	s_mov_b32 m0, s38
	s_nop 0
	global_load_lds_dwordx4 v[228:229], off
	v_add_u32_e32 v148, s70, v134
	v_add_u32_e32 v164, s71, v134
	ds_read_b128 v[136:139], v148
	ds_read_b128 v[140:143], v148 offset:1024
	ds_read_b128 v[144:147], v148 offset:2048
	ds_read_b128 v[148:151], v148 offset:3072
	ds_read_b128 v[152:155], v164
	ds_read_b128 v[156:159], v164 offset:1024
	ds_read_b128 v[160:163], v164 offset:2048
	ds_read_b128 v[164:167], v164 offset:3072
	ds_read_b128 v[168:171], v135 offset:32768
	ds_read_b128 v[174:177], v135 offset:33792
	ds_read_b128 v[180:183], v135 offset:34816
	ds_read_b128 v[188:191], v135 offset:35840
	ds_read_b128 v[204:207], v135 offset:36864
	ds_read_b128 v[208:211], v135 offset:37888
	ds_read_b128 v[212:215], v135 offset:38912
	ds_read_b128 v[216:219], v135 offset:39936
	s_waitcnt vmcnt(8)
	s_waitcnt lgkmcnt(0)
	s_barrier
	s_setprio 1
	s_waitcnt lgkmcnt(0)
	v_mfma_f32_16x16x32_bf16 v[124:127], v[136:139], v[168:171], v[124:127]
	v_mfma_f32_16x16x32_bf16 v[120:123], v[144:147], v[168:171], v[120:123]
	v_mfma_f32_16x16x32_bf16 v[116:119], v[136:139], v[180:183], v[116:119]
	v_mfma_f32_16x16x32_bf16 v[108:111], v[144:147], v[180:183], v[108:111]
	v_mfma_f32_16x16x32_bf16 v[100:103], v[136:139], v[204:207], v[100:103]
	v_mfma_f32_16x16x32_bf16 v[92:95], v[144:147], v[204:207], v[92:95]
	v_mfma_f32_16x16x32_bf16 v[84:87], v[136:139], v[212:215], v[84:87]
	v_mfma_f32_16x16x32_bf16 v[76:79], v[144:147], v[212:215], v[76:79]
	v_mfma_f32_16x16x32_bf16 v[124:127], v[140:143], v[174:177], v[124:127]
	v_mfma_f32_16x16x32_bf16 v[120:123], v[148:151], v[174:177], v[120:123]
	v_mfma_f32_16x16x32_bf16 v[116:119], v[140:143], v[188:191], v[116:119]
	v_mfma_f32_16x16x32_bf16 v[108:111], v[148:151], v[188:191], v[108:111]
	v_mfma_f32_16x16x32_bf16 v[100:103], v[140:143], v[208:211], v[100:103]
	v_mfma_f32_16x16x32_bf16 v[92:95], v[148:151], v[208:211], v[92:95]
	v_mfma_f32_16x16x32_bf16 v[84:87], v[140:143], v[216:219], v[84:87]
	v_mfma_f32_16x16x32_bf16 v[76:79], v[148:151], v[216:219], v[76:79]
	s_setprio 0
	s_setprio 1
	v_mfma_f32_16x16x32_bf16 v[112:115], v[152:155], v[168:171], v[112:115]
	v_mfma_f32_16x16x32_bf16 v[104:107], v[160:163], v[168:171], v[104:107]
	v_mfma_f32_16x16x32_bf16 v[96:99], v[152:155], v[180:183], v[96:99]
	v_mfma_f32_16x16x32_bf16 v[88:91], v[160:163], v[180:183], v[88:91]
	v_mfma_f32_16x16x32_bf16 v[80:83], v[152:155], v[204:207], v[80:83]
	v_mfma_f32_16x16x32_bf16 v[72:75], v[160:163], v[204:207], v[72:75]
	v_mfma_f32_16x16x32_bf16 v[68:71], v[152:155], v[212:215], v[68:71]
	v_mfma_f32_16x16x32_bf16 v[64:67], v[160:163], v[212:215], v[64:67]
	v_mfma_f32_16x16x32_bf16 v[112:115], v[156:159], v[174:177], v[112:115]
	v_mfma_f32_16x16x32_bf16 v[104:107], v[164:167], v[174:177], v[104:107]
	v_mfma_f32_16x16x32_bf16 v[96:99], v[156:159], v[188:191], v[96:99]
	v_mfma_f32_16x16x32_bf16 v[88:91], v[164:167], v[188:191], v[88:91]
	v_mfma_f32_16x16x32_bf16 v[80:83], v[156:159], v[208:211], v[80:83]
	v_mfma_f32_16x16x32_bf16 v[72:75], v[164:167], v[208:211], v[72:75]
	v_mfma_f32_16x16x32_bf16 v[68:71], v[156:159], v[216:219], v[68:71]
	v_mfma_f32_16x16x32_bf16 v[64:67], v[164:167], v[216:219], v[64:67]
	s_setprio 0
	s_barrier
	s_add_i32 s22, s70, s34
	v_lshl_add_u64 v[220:221], v[220:221], 0, s[94:95]
	s_mov_b32 m0, s22
	global_load_lds_dwordx4 v[220:221], off
	s_add_i32 m0, s22, 0x2000
	s_add_u32 s20, s20, 0xb0080
	v_lshl_add_u64 v[220:221], v[222:223], 0, s[94:95]
	s_addc_u32 s21, s21, 0
	s_add_i32 s22, s71, s34
	global_load_lds_dwordx4 v[220:221], off
	v_lshl_add_u64 v[220:221], s[20:21], 0, v[128:129]
	s_mov_b32 m0, s22
	s_nop 0
	global_load_lds_dwordx4 v[220:221], off
	v_lshl_add_u64 v[220:221], s[20:21], 0, v[132:133]
	s_add_i32 m0, s22, 0x2000
	s_nop 0
	global_load_lds_dwordx4 v[220:221], off
	v_lshl_add_u64 v[220:221], v[224:225], 0, s[94:95]
	s_mov_b32 m0, s55
	s_nop 0
	global_load_lds_dwordx4 v[220:221], off
	v_lshl_add_u64 v[220:221], v[226:227], 0, s[94:95]
	s_mov_b32 m0, s56
	s_nop 0
	global_load_lds_dwordx4 v[220:221], off
	ds_read_b128 v[168:171], v135 offset:49152
	ds_read_b128 v[174:177], v135 offset:50176
	ds_read_b128 v[180:183], v135 offset:51200
	ds_read_b128 v[188:191], v135 offset:52224
	ds_read_b128 v[204:207], v135 offset:53248
	ds_read_b128 v[208:211], v135 offset:54272
	ds_read_b128 v[212:215], v135 offset:55296
	ds_read_b128 v[216:219], v135 offset:56320
	s_waitcnt vmcnt(8)
	s_waitcnt lgkmcnt(0)
	s_barrier
	s_setprio 1
	s_waitcnt lgkmcnt(0)
	v_mfma_f32_16x16x32_bf16 v[60:63], v[136:139], v[168:171], v[60:63]
	v_mfma_f32_16x16x32_bf16 v[56:59], v[144:147], v[168:171], v[56:59]
	v_mfma_f32_16x16x32_bf16 v[52:55], v[136:139], v[180:183], v[52:55]
	v_mfma_f32_16x16x32_bf16 v[44:47], v[144:147], v[180:183], v[44:47]
	v_mfma_f32_16x16x32_bf16 v[36:39], v[136:139], v[204:207], v[36:39]
	v_mfma_f32_16x16x32_bf16 v[28:31], v[144:147], v[204:207], v[28:31]
	v_mfma_f32_16x16x32_bf16 v[20:23], v[136:139], v[212:215], v[20:23]
	v_mfma_f32_16x16x32_bf16 v[12:15], v[144:147], v[212:215], v[12:15]
	v_mfma_f32_16x16x32_bf16 v[60:63], v[140:143], v[174:177], v[60:63]
	v_mfma_f32_16x16x32_bf16 v[56:59], v[148:151], v[174:177], v[56:59]
	v_mfma_f32_16x16x32_bf16 v[52:55], v[140:143], v[188:191], v[52:55]
	v_mfma_f32_16x16x32_bf16 v[44:47], v[148:151], v[188:191], v[44:47]
	v_mfma_f32_16x16x32_bf16 v[36:39], v[140:143], v[208:211], v[36:39]
	v_mfma_f32_16x16x32_bf16 v[28:31], v[148:151], v[208:211], v[28:31]
	v_mfma_f32_16x16x32_bf16 v[20:23], v[140:143], v[216:219], v[20:23]
	v_mfma_f32_16x16x32_bf16 v[12:15], v[148:151], v[216:219], v[12:15]
	s_setprio 0
	s_setprio 1
	v_mfma_f32_16x16x32_bf16 v[48:51], v[152:155], v[168:171], v[48:51]
	v_mfma_f32_16x16x32_bf16 v[40:43], v[160:163], v[168:171], v[40:43]
	v_mfma_f32_16x16x32_bf16 v[32:35], v[152:155], v[180:183], v[32:35]
	v_mfma_f32_16x16x32_bf16 v[24:27], v[160:163], v[180:183], v[24:27]
	v_mfma_f32_16x16x32_bf16 v[16:19], v[152:155], v[204:207], v[16:19]
	v_mfma_f32_16x16x32_bf16 v[8:11], v[160:163], v[204:207], v[8:11]
	v_mfma_f32_16x16x32_bf16 v[4:7], v[152:155], v[212:215], v[4:7]
	v_mfma_f32_16x16x32_bf16 v[0:3], v[160:163], v[212:215], v[0:3]
	v_mfma_f32_16x16x32_bf16 v[48:51], v[156:159], v[174:177], v[48:51]
	v_mfma_f32_16x16x32_bf16 v[40:43], v[164:167], v[174:177], v[40:43]
	v_mfma_f32_16x16x32_bf16 v[32:35], v[156:159], v[188:191], v[32:35]
	v_mfma_f32_16x16x32_bf16 v[24:27], v[164:167], v[188:191], v[24:27]
	v_mfma_f32_16x16x32_bf16 v[16:19], v[156:159], v[208:211], v[16:19]
	v_mfma_f32_16x16x32_bf16 v[8:11], v[164:167], v[208:211], v[8:11]
	v_mfma_f32_16x16x32_bf16 v[4:7], v[156:159], v[216:219], v[4:7]
	v_mfma_f32_16x16x32_bf16 v[0:3], v[164:167], v[216:219], v[0:3]
	s_setprio 0
	s_barrier
	s_add_u32 s6, s6, 0x100
	s_addc_u32 s7, s7, 0
	s_add_u32 s25, s25, 0x100
	s_addc_u32 s68, s68, 0
	s_cmp_ge_i32 s69, s65
	s_mov_b32 s20, s69
	s_cbranch_scc0 .LBB0_1057
	s_and_b64 vcc, exec, s[14:15]
	s_cbranch_vccz .LBB0_1060
	s_barrier
